# conversion loop: counted vmcnt + incremental store addresses with 3-deep LDS read pipelining; G1/G2b/G4 K-loops: first iteration peeled with C=0 instead of v_mov zeroing
# speedup vs baseline: 1.0028x; 1.0028x over previous
; #define GPROBE_BEGIN(id) do { if (((PROBE_GEMM_SEL >> (id)) & 1) && blockIdx.x == 0 && tid_in < 64 && g.N == 20480) { volatile PG8_LAS unsigned long long* PW_ = (volatile PG8_LAS unsigned long long*)(lds + 163840 - 512 + 64); PW_[0] = __builtin_amdgcn_s_memrealtime(); } } while (0)
; #define GPROBE_END(id) do { if (((PROBE_GEMM_SEL >> (id)) & 1) && blockIdx.x == 0 && tid_in < 64 && g.N == 20480) { volatile PG8_LAS unsigned long long* PW_ = (volatile PG8_LAS unsigned long long*)(lds + 163840 - 512 + 64); PW_[1] += __builtin_amdgcn_s_memrealtime() - PW_[0]; } } while (0)
; #define PG8_BAR __builtin_amdgcn_s_barrier()
; template <class Epi, class Sched, bool ALIGN_EPI = false, bool SP2 = false, bool KHOOK = false>
; __device__ __forceinline__ void gemm_phase(PG8_LAS unsigned char* lds, const Gemm g, const Sched& S, const Epi& E, const int tid_in) {
;     ...
;         const char* nA = has_next ? (const char*)g.A + (size_t)nxt.pm * tstep + (size_t)nxt.pn * ksl : cA; const char* nB = has_next ? (const char*)g.Bt + (size_t)nxt.pn * bts + (size_t)nxt.pn * ksl + (gdv ? (size_t)(nxt.pm / gdv) * gst : 0) : cB;
;         GPROBE_END(2); GPROBE_BEGIN(1);
;         for (int t = 0; t < nt; t += 2) {
;             const bool last = (t == nt - 2);
;             const char* a1 = cA + (size_t)(t + 1) * kstep;
;             const char* a2 = last ? nA : cA + (size_t)(t + 2) * kstep; const char* b2 = last ? nB : cB + (size_t)(t + 2) * kstep;
;             const char* a3 = a2 + kstep; const char* b3 = b2 + kstep;
;             if (last && has_next) S.a_ready(nxt);
;             if constexpr (SP2) {
;             PG8_LDB(B0, 0, 0); PG8_LDB(B1, 0, 1); PG8_SCHED; PG8_LDA(At, 0, 0); PG8_STAGE(PG8_SA(1, 1), a1 + hstep, voffA);
;             PG8_WAIT_V(8); PG8_WAIT_L(0); PG8_BAR; PG8_MMA(0, 0, At, B0); PG8_MMA(0, 1, At, B1); PG8_BAR; PG8_SCHED;
;             PG8_LDA(At, 0, 1); PG8_STAGE(PG8_SB(0, 0), b2, voffB); PG8_STAGE(PG8_SB(0, 1), b2 + hstep, voffB); PG8_STAGE(PG8_SA(0, 0), a2, voffA);
;             PG8_WAIT_V(8); PG8_WAIT_L(0); PG8_BAR; PG8_MMA(1, 0, At, B0); PG8_MMA(1, 1, At, B1); PG8_BAR; PG8_SCHED;
;     ...
; #pragma unroll
;         for (int a = 0; a < 2; ++a)
; #pragma unroll
;             for (int b = 0; b < 2; ++b)
; #pragma unroll
;                 for (int m = 0; m < 4; ++m)
; #pragma unroll
;                     for (int n = 0; n < 2; ++n) acc[a][b][m][n] = (f32x4){0.f, 0.f, 0.f, 0.f};
.LBB0_262:
	s_ashr_i32 s17, s16, 31
	s_lshl_b64 s[18:19], s[16:17], 20
	s_add_u32 s26, s78, s18
	s_addc_u32 s27, s79, s19
	s_and_b64 s[18:19], s[22:23], exec
	s_cselect_b32 s11, s27, s49
	s_cselect_b32 s17, s26, s48
	s_ashr_i32 s15, s14, 31
	s_lshl_b64 s[18:19], s[14:15], 20
	v_readlane_b32 s5, v255, 25
	s_add_u32 s30, s5, s18
	v_readlane_b32 s5, v255, 26
	s_addc_u32 s31, s5, s19
	s_and_b64 s[18:19], s[22:23], exec
	s_cselect_b32 s15, s31, s53
	s_cselect_b32 s18, s30, s52
	s_add_u32 s48, s48, 0x80080
	s_addc_u32 s49, s49, 0
	s_add_u32 s19, s52, 0x100
	s_addc_u32 s42, s53, 0
	s_mov_b32 s44, -2
	s_add_u32 s45, s48, 0xfff80080
	s_addc_u32 s46, s49, -1
	s_add_i32 s47, 0, 0x10000
	s_cmp_eq_u32 s44, 28
	s_cselect_b32 s57, s11, s46
	s_cselect_b32 s56, s17, s45
	s_cselect_b32 s53, s15, s42
	s_cselect_b32 s52, s18, s19
	s_add_i32 s45, 0, 0x14000
	v_add_u32_e32 v156, s47, v141
	v_add_u32_e32 v172, s45, v141
	ds_read_b128 v[144:147], v156
	ds_read_b128 v[148:151], v156 offset:1024
	ds_read_b128 v[152:155], v156 offset:2048
	ds_read_b128 v[156:159], v156 offset:3072
	ds_read_b128 v[160:163], v172
	ds_read_b128 v[164:167], v172 offset:1024
	ds_read_b128 v[168:171], v172 offset:2048
	ds_read_b128 v[172:175], v172 offset:3072
	v_lshl_add_u64 v[192:193], s[48:49], 0, v[136:137]
	s_add_i32 m0, s13, 0xc000
	ds_read_b128 v[176:179], v143
	ds_read_b128 v[180:183], v143 offset:1024
	ds_read_b128 v[184:187], v143 offset:2048
	ds_read_b128 v[188:191], v143 offset:3072
	ds_read_b128 v[198:201], v143 offset:4096
	ds_read_b128 v[202:205], v143 offset:5120
	ds_read_b128 v[206:209], v143 offset:6144
	ds_read_b128 v[210:213], v143 offset:7168
	global_load_lds_dwordx4 v[192:193], off
	v_lshl_add_u64 v[192:193], s[48:49], 0, v[138:139]
	s_add_i32 m0, s13, 0xe000
	s_nop 0
	global_load_lds_dwordx4 v[192:193], off
	s_waitcnt vmcnt(8)
	s_waitcnt lgkmcnt(0)
	s_barrier
	s_setprio 1
	s_waitcnt lgkmcnt(0)
	v_mfma_f32_16x16x32_bf16 v[126:129], v[144:147], v[176:179], 0
	v_mfma_f32_16x16x32_bf16 v[122:125], v[152:155], v[176:179], 0
	v_mfma_f32_16x16x32_bf16 v[118:121], v[144:147], v[184:187], 0
	v_mfma_f32_16x16x32_bf16 v[114:117], v[152:155], v[184:187], 0
	v_mfma_f32_16x16x32_bf16 v[102:105], v[144:147], v[198:201], 0
	v_mfma_f32_16x16x32_bf16 v[98:101], v[152:155], v[198:201], 0
	v_mfma_f32_16x16x32_bf16 v[86:89], v[144:147], v[206:209], 0
	v_mfma_f32_16x16x32_bf16 v[82:85], v[152:155], v[206:209], 0
	v_mfma_f32_16x16x32_bf16 v[126:129], v[148:151], v[180:183], v[126:129]
	v_mfma_f32_16x16x32_bf16 v[122:125], v[156:159], v[180:183], v[122:125]
	v_mfma_f32_16x16x32_bf16 v[118:121], v[148:151], v[188:191], v[118:121]
	v_mfma_f32_16x16x32_bf16 v[114:117], v[156:159], v[188:191], v[114:117]
	v_mfma_f32_16x16x32_bf16 v[102:105], v[148:151], v[202:205], v[102:105]
	v_mfma_f32_16x16x32_bf16 v[98:101], v[156:159], v[202:205], v[98:101]
	v_mfma_f32_16x16x32_bf16 v[86:89], v[148:151], v[210:213], v[86:89]
	v_mfma_f32_16x16x32_bf16 v[82:85], v[156:159], v[210:213], v[82:85]
	s_setprio 0
	s_setprio 1
	v_mfma_f32_16x16x32_bf16 v[110:113], v[160:163], v[176:179], 0
	v_mfma_f32_16x16x32_bf16 v[106:109], v[168:171], v[176:179], 0
	v_mfma_f32_16x16x32_bf16 v[94:97], v[160:163], v[184:187], 0
	v_mfma_f32_16x16x32_bf16 v[90:93], v[168:171], v[184:187], 0
	v_mfma_f32_16x16x32_bf16 v[78:81], v[160:163], v[198:201], 0
	v_mfma_f32_16x16x32_bf16 v[74:77], v[168:171], v[198:201], 0
	v_mfma_f32_16x16x32_bf16 v[70:73], v[160:163], v[206:209], 0
	v_mfma_f32_16x16x32_bf16 v[66:69], v[168:171], v[206:209], 0
	v_mfma_f32_16x16x32_bf16 v[110:113], v[164:167], v[180:183], v[110:113]
	v_mfma_f32_16x16x32_bf16 v[106:109], v[172:175], v[180:183], v[106:109]
	v_mfma_f32_16x16x32_bf16 v[94:97], v[164:167], v[188:191], v[94:97]
	v_mfma_f32_16x16x32_bf16 v[90:93], v[172:175], v[188:191], v[90:93]
	v_mfma_f32_16x16x32_bf16 v[78:81], v[164:167], v[202:205], v[78:81]
	v_mfma_f32_16x16x32_bf16 v[74:77], v[172:175], v[202:205], v[74:77]
	v_mfma_f32_16x16x32_bf16 v[70:73], v[164:167], v[210:213], v[70:73]
	v_mfma_f32_16x16x32_bf16 v[66:69], v[172:175], v[210:213], v[66:69]
	s_setprio 0
	s_barrier
	s_add_i32 s46, s47, s37
	v_lshl_add_u64 v[192:193], s[52:53], 0, v[32:33]
	s_mov_b32 m0, s46
	ds_read_b128 v[176:179], v143 offset:16384
	ds_read_b128 v[180:183], v143 offset:17408
	ds_read_b128 v[184:187], v143 offset:18432
	ds_read_b128 v[188:191], v143 offset:19456
	ds_read_b128 v[198:201], v143 offset:20480
	ds_read_b128 v[202:205], v143 offset:21504
	ds_read_b128 v[206:209], v143 offset:22528
	ds_read_b128 v[210:213], v143 offset:23552
	global_load_lds_dwordx4 v[192:193], off
	s_add_i32 m0, s46, 0x2000
	s_add_u32 s46, s52, 0x80000
	v_lshl_add_u64 v[214:215], s[52:53], 0, v[134:135]
	s_addc_u32 s47, s53, 0
	s_add_i32 s45, s45, s37
	global_load_lds_dwordx4 v[214:215], off
	v_lshl_add_u64 v[216:217], s[46:47], 0, v[32:33]
	s_mov_b32 m0, s45
	v_lshl_add_u64 v[218:219], s[56:57], 0, v[132:133]
	global_load_lds_dwordx4 v[216:217], off
	v_lshl_add_u64 v[216:217], s[46:47], 0, v[134:135]
	s_add_i32 m0, s45, 0x2000
	s_nop 0
	global_load_lds_dwordx4 v[216:217], off
	v_lshl_add_u64 v[216:217], s[56:57], 0, v[130:131]
	s_mov_b32 m0, s13
	s_nop 0
	global_load_lds_dwordx4 v[216:217], off
	s_mov_b32 m0, s24
	s_nop 0
	global_load_lds_dwordx4 v[218:219], off
	s_waitcnt vmcnt(8)
	s_waitcnt lgkmcnt(0)
	s_barrier
; #define PG8_STAGE(bufoff, gbase, voff) do { _Pragma("unroll") for (int _i = 0; _i < 2; ++_i) \
;         __builtin_amdgcn_global_load_lds((const unsigned*)((const char*)(gbase) + (voff)[_i]), (PG8_LAS unsigned*)(lds + (bufoff) + ldsw + _i * 8192), 16, 0, 0); } while (0)
; #define PG8_LDA(dst, b, h) do { _Pragma("unroll") for (int m = 0; m < 4; ++m) _Pragma("unroll") for (int k = 0; k < 2; ++k) dst[m][k] = *(const PG8_LAS bf16x8*)(lds + PG8_SA(b, h) + aoff + m * 2048 + k * 1024); } while (0)
; #define PG8_LDB(dst, b, h) do { _Pragma("unroll") for (int n = 0; n < 2; ++n) _Pragma("unroll") for (int k = 0; k < 2; ++k) dst[n][k] = *(const PG8_LAS bf16x8*)(lds + PG8_SB(b, h) + boff + n * 2048 + k * 1024); } while (0)
; #define PG8_MMA(ai, bj, At, Bt) do { __builtin_amdgcn_s_setprio(1); _Pragma("unroll") for (int m = 0; m < 4; ++m) _Pragma("unroll") for (int n = 0; n < 2; ++n) _Pragma("unroll") for (int k = 0; k < 2; ++k) \
;         acc[ai][bj][m][n] = __builtin_amdgcn_mfma_f32_16x16x32_bf16(Bt[n][k], At[m][k], acc[ai][bj][m][n], 0, 0, 0); __builtin_amdgcn_s_setprio(0); } while (0)
; #define PG8_WAIT_V(n) asm volatile("s_waitcnt vmcnt(" #n ")" ::: "memory")
; #define PG8_WAIT_L(n) asm volatile("s_waitcnt lgkmcnt(" #n ")" ::: "memory")
; #define PG8_BAR __builtin_amdgcn_s_barrier()
; #define PG8_SCHED __builtin_amdgcn_sched_barrier(0)
; template <class Epi, class Sched, bool ALIGN_EPI = false, bool SP2 = false, bool KHOOK = false>
; __device__ __forceinline__ void gemm_phase(PG8_LAS unsigned char* lds, const Gemm g, const Sched& S, const Epi& E, const int tid_in) {
;     ...
;             PG8_WAIT_V(8); PG8_WAIT_L(0); PG8_BAR; PG8_MMA(1, 0, At, B0); PG8_MMA(1, 1, At, B1); PG8_BAR; PG8_SCHED;
;             PG8_LDB(B0, 1, 0); PG8_LDB(B1, 1, 1); PG8_SCHED; PG8_LDA(At, 1, 0); PG8_STAGE(PG8_SA(0, 1), a2 + hstep, voffA);
;             PG8_WAIT_V(8); PG8_WAIT_L(0); PG8_BAR; PG8_MMA(0, 0, At, B0); PG8_MMA(0, 1, At, B1); PG8_BAR; PG8_SCHED;
	s_setprio 1
	s_waitcnt lgkmcnt(0)
	v_mfma_f32_16x16x32_bf16 v[62:65], v[144:147], v[176:179], 0
	v_mfma_f32_16x16x32_bf16 v[58:61], v[152:155], v[176:179], 0
	v_mfma_f32_16x16x32_bf16 v[54:57], v[144:147], v[184:187], 0
	v_mfma_f32_16x16x32_bf16 v[50:53], v[152:155], v[184:187], 0
	v_mfma_f32_16x16x32_bf16 v[38:41], v[144:147], v[198:201], 0
	v_mfma_f32_16x16x32_bf16 v[34:37], v[152:155], v[198:201], 0
	v_mfma_f32_16x16x32_bf16 v[20:23], v[144:147], v[206:209], 0
	v_mfma_f32_16x16x32_bf16 v[16:19], v[152:155], v[206:209], 0
	v_mfma_f32_16x16x32_bf16 v[62:65], v[148:151], v[180:183], v[62:65]
	v_mfma_f32_16x16x32_bf16 v[58:61], v[156:159], v[180:183], v[58:61]
	v_mfma_f32_16x16x32_bf16 v[54:57], v[148:151], v[188:191], v[54:57]
	v_mfma_f32_16x16x32_bf16 v[50:53], v[156:159], v[188:191], v[50:53]
	v_mfma_f32_16x16x32_bf16 v[38:41], v[148:151], v[202:205], v[38:41]
	v_mfma_f32_16x16x32_bf16 v[34:37], v[156:159], v[202:205], v[34:37]
	v_mfma_f32_16x16x32_bf16 v[20:23], v[148:151], v[210:213], v[20:23]
	v_mfma_f32_16x16x32_bf16 v[16:19], v[156:159], v[210:213], v[16:19]
	s_setprio 0
	s_setprio 1
	v_mfma_f32_16x16x32_bf16 v[46:49], v[160:163], v[176:179], 0
	v_mfma_f32_16x16x32_bf16 v[42:45], v[168:171], v[176:179], 0
	v_mfma_f32_16x16x32_bf16 v[28:31], v[160:163], v[184:187], 0
	v_mfma_f32_16x16x32_bf16 v[24:27], v[168:171], v[184:187], 0
	v_mfma_f32_16x16x32_bf16 v[12:15], v[160:163], v[198:201], 0
	v_mfma_f32_16x16x32_bf16 v[8:11], v[168:171], v[198:201], 0
	v_mfma_f32_16x16x32_bf16 v[4:7], v[160:163], v[206:209], 0
	v_mfma_f32_16x16x32_bf16 v[0:3], v[168:171], v[206:209], 0
	v_mfma_f32_16x16x32_bf16 v[46:49], v[164:167], v[180:183], v[46:49]
	v_mfma_f32_16x16x32_bf16 v[42:45], v[172:175], v[180:183], v[42:45]
	v_mfma_f32_16x16x32_bf16 v[28:31], v[164:167], v[188:191], v[28:31]
	v_mfma_f32_16x16x32_bf16 v[24:27], v[172:175], v[188:191], v[24:27]
	v_mfma_f32_16x16x32_bf16 v[12:15], v[164:167], v[202:205], v[12:15]
	v_mfma_f32_16x16x32_bf16 v[8:11], v[172:175], v[202:205], v[8:11]
	v_mfma_f32_16x16x32_bf16 v[4:7], v[164:167], v[210:213], v[4:7]
	v_mfma_f32_16x16x32_bf16 v[0:3], v[172:175], v[210:213], v[0:3]
	s_setprio 0
	s_barrier
	s_add_i32 s45, 0, 0x18000
	s_add_i32 s50, 0, 0x1c000
	v_add_u32_e32 v156, s45, v141
	v_add_u32_e32 v172, s50, v141
	ds_read_b128 v[144:147], v156
	ds_read_b128 v[148:151], v156 offset:1024
	ds_read_b128 v[152:155], v156 offset:2048
	ds_read_b128 v[156:159], v156 offset:3072
	ds_read_b128 v[160:163], v172
	ds_read_b128 v[164:167], v172 offset:1024
	ds_read_b128 v[168:171], v172 offset:2048
	ds_read_b128 v[172:175], v172 offset:3072
	s_add_u32 s46, s56, 0x80000
	s_addc_u32 s47, s57, 0
	s_mov_b32 m0, s25
	v_lshl_add_u64 v[220:221], s[46:47], 0, v[130:131]
	ds_read_b128 v[176:179], v143 offset:32768
	ds_read_b128 v[180:183], v143 offset:33792
	ds_read_b128 v[184:187], v143 offset:34816
	ds_read_b128 v[188:191], v143 offset:35840
	ds_read_b128 v[198:201], v143 offset:36864
	ds_read_b128 v[202:205], v143 offset:37888
	ds_read_b128 v[206:209], v143 offset:38912
	ds_read_b128 v[210:213], v143 offset:39936
	global_load_lds_dwordx4 v[220:221], off
	v_lshl_add_u64 v[220:221], s[46:47], 0, v[132:133]
	s_mov_b32 m0, s38
	s_nop 0
	global_load_lds_dwordx4 v[220:221], off
	s_waitcnt vmcnt(8)
	s_waitcnt lgkmcnt(0)
	s_barrier
	s_setprio 1
	s_waitcnt lgkmcnt(0)
	v_mfma_f32_16x16x32_bf16 v[126:129], v[144:147], v[176:179], v[126:129]
	v_mfma_f32_16x16x32_bf16 v[122:125], v[152:155], v[176:179], v[122:125]
	v_mfma_f32_16x16x32_bf16 v[118:121], v[144:147], v[184:187], v[118:121]
	v_mfma_f32_16x16x32_bf16 v[114:117], v[152:155], v[184:187], v[114:117]
	v_mfma_f32_16x16x32_bf16 v[102:105], v[144:147], v[198:201], v[102:105]
	v_mfma_f32_16x16x32_bf16 v[98:101], v[152:155], v[198:201], v[98:101]
	v_mfma_f32_16x16x32_bf16 v[86:89], v[144:147], v[206:209], v[86:89]
	v_mfma_f32_16x16x32_bf16 v[82:85], v[152:155], v[206:209], v[82:85]
	v_mfma_f32_16x16x32_bf16 v[126:129], v[148:151], v[180:183], v[126:129]
	v_mfma_f32_16x16x32_bf16 v[122:125], v[156:159], v[180:183], v[122:125]
	v_mfma_f32_16x16x32_bf16 v[118:121], v[148:151], v[188:191], v[118:121]
	v_mfma_f32_16x16x32_bf16 v[114:117], v[156:159], v[188:191], v[114:117]
	v_mfma_f32_16x16x32_bf16 v[102:105], v[148:151], v[202:205], v[102:105]
	v_mfma_f32_16x16x32_bf16 v[98:101], v[156:159], v[202:205], v[98:101]
	v_mfma_f32_16x16x32_bf16 v[86:89], v[148:151], v[210:213], v[86:89]
	v_mfma_f32_16x16x32_bf16 v[82:85], v[156:159], v[210:213], v[82:85]
	s_setprio 0
	s_setprio 1
	v_mfma_f32_16x16x32_bf16 v[110:113], v[160:163], v[176:179], v[110:113]
	v_mfma_f32_16x16x32_bf16 v[106:109], v[168:171], v[176:179], v[106:109]
	v_mfma_f32_16x16x32_bf16 v[94:97], v[160:163], v[184:187], v[94:97]
	v_mfma_f32_16x16x32_bf16 v[90:93], v[168:171], v[184:187], v[90:93]
	v_mfma_f32_16x16x32_bf16 v[78:81], v[160:163], v[198:201], v[78:81]
	v_mfma_f32_16x16x32_bf16 v[74:77], v[168:171], v[198:201], v[74:77]
	v_mfma_f32_16x16x32_bf16 v[70:73], v[160:163], v[206:209], v[70:73]
	v_mfma_f32_16x16x32_bf16 v[66:69], v[168:171], v[206:209], v[66:69]
	v_mfma_f32_16x16x32_bf16 v[110:113], v[164:167], v[180:183], v[110:113]
	v_mfma_f32_16x16x32_bf16 v[106:109], v[172:175], v[180:183], v[106:109]
	v_mfma_f32_16x16x32_bf16 v[94:97], v[164:167], v[188:191], v[94:97]
	v_mfma_f32_16x16x32_bf16 v[90:93], v[172:175], v[188:191], v[90:93]
	v_mfma_f32_16x16x32_bf16 v[78:81], v[164:167], v[202:205], v[78:81]
	v_mfma_f32_16x16x32_bf16 v[74:77], v[172:175], v[202:205], v[74:77]
	v_mfma_f32_16x16x32_bf16 v[70:73], v[164:167], v[210:213], v[70:73]
	v_mfma_f32_16x16x32_bf16 v[66:69], v[172:175], v[210:213], v[66:69]
	s_setprio 0
	s_barrier
; #define PG8_STAGE(bufoff, gbase, voff) do { _Pragma("unroll") for (int _i = 0; _i < 2; ++_i) \
;         __builtin_amdgcn_global_load_lds((const unsigned*)((const char*)(gbase) + (voff)[_i]), (PG8_LAS unsigned*)(lds + (bufoff) + ldsw + _i * 8192), 16, 0, 0); } while (0)
; #define PG8_LDA(dst, b, h) do { _Pragma("unroll") for (int m = 0; m < 4; ++m) _Pragma("unroll") for (int k = 0; k < 2; ++k) dst[m][k] = *(const PG8_LAS bf16x8*)(lds + PG8_SA(b, h) + aoff + m * 2048 + k * 1024); } while (0)
; #define PG8_MMA(ai, bj, At, Bt) do { __builtin_amdgcn_s_setprio(1); _Pragma("unroll") for (int m = 0; m < 4; ++m) _Pragma("unroll") for (int n = 0; n < 2; ++n) _Pragma("unroll") for (int k = 0; k < 2; ++k) \
;         acc[ai][bj][m][n] = __builtin_amdgcn_mfma_f32_16x16x32_bf16(Bt[n][k], At[m][k], acc[ai][bj][m][n], 0, 0, 0); __builtin_amdgcn_s_setprio(0); } while (0)
; #define PG8_WAIT_V(n) asm volatile("s_waitcnt vmcnt(" #n ")" ::: "memory")
; #define PG8_WAIT_L(n) asm volatile("s_waitcnt lgkmcnt(" #n ")" ::: "memory")
; #define PG8_BAR __builtin_amdgcn_s_barrier()
; #define PG8_SCHED __builtin_amdgcn_sched_barrier(0)
; template <class Epi, class Sched, bool ALIGN_EPI = false, bool SP2 = false, bool KHOOK = false>
; __device__ __forceinline__ void gemm_phase(PG8_LAS unsigned char* lds, const Gemm g, const Sched& S, const Epi& E, const int tid_in) {
;     ...
;         for (int t = 0; t < nt; t += 2) {
;             const bool last = (t == nt - 2);
;             const char* a1 = cA + (size_t)(t + 1) * kstep;
;             const char* a2 = last ? nA : cA + (size_t)(t + 2) * kstep; const char* b2 = last ? nB : cB + (size_t)(t + 2) * kstep;
;     ...
;             PG8_LDA(At, 1, 1); PG8_STAGE(PG8_SB(1, 0), b3, voffB); PG8_STAGE(PG8_SB(1, 1), b3 + hstep, voffB); PG8_STAGE(PG8_SA(1, 0), a3, voffA);
;             PG8_WAIT_V(8); PG8_WAIT_L(0); PG8_BAR; PG8_MMA(1, 0, At, B0); PG8_MMA(1, 1, At, B1); PG8_BAR; PG8_SCHED;
	s_add_i32 s45, s45, s37
	v_lshl_add_u64 v[192:193], v[192:193], 0, s[90:91]
	s_mov_b32 m0, s45
	ds_read_b128 v[176:179], v143 offset:49152
	ds_read_b128 v[180:183], v143 offset:50176
	ds_read_b128 v[184:187], v143 offset:51200
	ds_read_b128 v[188:191], v143 offset:52224
	ds_read_b128 v[198:201], v143 offset:53248
	ds_read_b128 v[202:205], v143 offset:54272
	ds_read_b128 v[206:209], v143 offset:55296
	ds_read_b128 v[210:213], v143 offset:56320
	global_load_lds_dwordx4 v[192:193], off
	s_add_i32 m0, s45, 0x2000
	s_add_u32 s46, s52, 0x80080
	v_lshl_add_u64 v[192:193], v[214:215], 0, s[90:91]
	s_addc_u32 s47, s53, 0
	s_add_i32 s45, s50, s37
	global_load_lds_dwordx4 v[192:193], off
	v_lshl_add_u64 v[192:193], s[46:47], 0, v[32:33]
	s_mov_b32 m0, s45
	s_nop 0
	global_load_lds_dwordx4 v[192:193], off
	v_lshl_add_u64 v[192:193], s[46:47], 0, v[134:135]
	s_add_i32 m0, s45, 0x2000
	s_nop 0
	global_load_lds_dwordx4 v[192:193], off
	v_lshl_add_u64 v[192:193], v[216:217], 0, s[90:91]
	s_mov_b32 m0, s39
	s_nop 0
	global_load_lds_dwordx4 v[192:193], off
	v_lshl_add_u64 v[192:193], v[218:219], 0, s[90:91]
	s_mov_b32 m0, s40
	s_nop 0
	global_load_lds_dwordx4 v[192:193], off
	s_waitcnt vmcnt(8)
	s_waitcnt lgkmcnt(0)
	s_barrier
	s_setprio 1
	s_waitcnt lgkmcnt(0)
	v_mfma_f32_16x16x32_bf16 v[62:65], v[144:147], v[176:179], v[62:65]
	v_mfma_f32_16x16x32_bf16 v[58:61], v[152:155], v[176:179], v[58:61]
	v_mfma_f32_16x16x32_bf16 v[54:57], v[144:147], v[184:187], v[54:57]
	v_mfma_f32_16x16x32_bf16 v[50:53], v[152:155], v[184:187], v[50:53]
	v_mfma_f32_16x16x32_bf16 v[38:41], v[144:147], v[198:201], v[38:41]
	v_mfma_f32_16x16x32_bf16 v[34:37], v[152:155], v[198:201], v[34:37]
	v_mfma_f32_16x16x32_bf16 v[20:23], v[144:147], v[206:209], v[20:23]
	v_mfma_f32_16x16x32_bf16 v[16:19], v[152:155], v[206:209], v[16:19]
	v_mfma_f32_16x16x32_bf16 v[62:65], v[148:151], v[180:183], v[62:65]
	v_mfma_f32_16x16x32_bf16 v[58:61], v[156:159], v[180:183], v[58:61]
	v_mfma_f32_16x16x32_bf16 v[54:57], v[148:151], v[188:191], v[54:57]
	v_mfma_f32_16x16x32_bf16 v[50:53], v[156:159], v[188:191], v[50:53]
	v_mfma_f32_16x16x32_bf16 v[38:41], v[148:151], v[202:205], v[38:41]
	v_mfma_f32_16x16x32_bf16 v[34:37], v[156:159], v[202:205], v[34:37]
	v_mfma_f32_16x16x32_bf16 v[20:23], v[148:151], v[210:213], v[20:23]
	v_mfma_f32_16x16x32_bf16 v[16:19], v[156:159], v[210:213], v[16:19]
	s_setprio 0
	s_setprio 1
	v_mfma_f32_16x16x32_bf16 v[46:49], v[160:163], v[176:179], v[46:49]
	v_mfma_f32_16x16x32_bf16 v[42:45], v[168:171], v[176:179], v[42:45]
	v_mfma_f32_16x16x32_bf16 v[28:31], v[160:163], v[184:187], v[28:31]
	v_mfma_f32_16x16x32_bf16 v[24:27], v[168:171], v[184:187], v[24:27]
	v_mfma_f32_16x16x32_bf16 v[12:15], v[160:163], v[198:201], v[12:15]
	v_mfma_f32_16x16x32_bf16 v[8:11], v[168:171], v[198:201], v[8:11]
	v_mfma_f32_16x16x32_bf16 v[4:7], v[160:163], v[206:209], v[4:7]
	v_mfma_f32_16x16x32_bf16 v[0:3], v[168:171], v[206:209], v[0:3]
	v_mfma_f32_16x16x32_bf16 v[46:49], v[164:167], v[180:183], v[46:49]
	v_mfma_f32_16x16x32_bf16 v[42:45], v[172:175], v[180:183], v[42:45]
	v_mfma_f32_16x16x32_bf16 v[28:31], v[164:167], v[188:191], v[28:31]
	v_mfma_f32_16x16x32_bf16 v[24:27], v[172:175], v[188:191], v[24:27]
	v_mfma_f32_16x16x32_bf16 v[12:15], v[164:167], v[202:205], v[12:15]
	v_mfma_f32_16x16x32_bf16 v[8:11], v[172:175], v[202:205], v[8:11]
	v_mfma_f32_16x16x32_bf16 v[4:7], v[164:167], v[210:213], v[4:7]
	v_mfma_f32_16x16x32_bf16 v[0:3], v[172:175], v[210:213], v[0:3]
	s_setprio 0
	s_barrier
	s_add_i32 s44, s44, 2
	s_add_u32 s48, s48, 0x100
	s_addc_u32 s49, s49, 0
	s_add_u32 s19, s19, 0x100
	s_addc_u32 s42, s42, 0
	s_cmp_gt_u32 s44, 29

; #define LAS __attribute__((address_space(3)))
; __device__ __forceinline__ void item_store(const TItem& t, LAS float* scr, int lane) {
;     ...
;     const int c = lane & 7, nn = lane >> 3;
; #pragma unroll
;     for (int j = 0; j < 8; ++j) { const int n = nn + 8 * j; const LAS float* s = scr + (8 * c) * 65 + n;
;     ...
;         int it = it0; TItem cur = decode(it); float v[64]; float kv; item_load(cur, v, kv, lane);
;         for (;;) {
;             if (cur.ks) {
; #pragma unroll
;                 for (int i = 0; i < 64; ++i) scr[i * 65 + lane] = v[i] * __shfl(kv, i);
.LBB0_301:
	v_ashrrev_i32_e32 v12, 3, v0
	v_lshlrev_b32_e32 v2, 3, v0
	v_and_b32_e32 v2, 56, v2
	v_lshlrev_b32_e32 v5, 5, v12
	v_readlane_b32 s4, v252, 26
	v_mul_u32_u24_e32 v4, 0x104, v2
	v_and_b32_e32 v13, 0x80, v5
	v_lshlrev_b32_e32 v5, 2, v12
	v_add_u32_e32 v15, 8, v12
	v_add3_u32 v14, s4, v4, v5
	v_lshrrev_b32_e32 v5, 1, v15
	v_add_u32_e32 v17, 16, v12
	v_and_b32_e32 v16, 12, v5
	v_lshrrev_b32_e32 v5, 1, v17
	v_add_u32_e32 v19, 24, v12
	v_and_b32_e32 v18, 12, v5
	v_lshrrev_b32_e32 v5, 1, v19
	v_add_u32_e32 v21, 40, v12
	v_and_b32_e32 v20, 12, v5
	v_lshrrev_b32_e32 v5, 1, v21
	v_add_u32_e32 v23, 48, v12
	v_and_b32_e32 v22, 12, v5
	v_lshrrev_b32_e32 v5, 1, v23
	v_add_u32_e32 v25, 56, v12
	v_lshrrev_b32_e32 v4, 1, v12
	v_and_b32_e32 v24, 12, v5
	v_lshrrev_b32_e32 v5, 1, v25
	v_lshl_add_u32 v3, v0, 2, s4
	v_and_b32_e32 v26, 12, v5
	v_and_or_b32 v27, v4, 12, v13
	s_waitcnt vmcnt(0)
	s_branch .LBB0_304
.Lconv_tail_g1:
	s_waitcnt lgkmcnt(0)
	s_mov_b32 s38, s18
	v_readlane_b32 s16, v255, 2
	s_andn2_b64 vcc, exec, s[46:47]
	s_mov_b32 s39, s40
	s_mov_b32 s44, s16
	s_mov_b32 s37, s41
	s_mov_b64 s[6:7], s[14:15]
	v_readlane_b32 s17, v255, 3
	v_readlane_b32 s18, v255, 4
	v_readlane_b32 s19, v255, 5
	s_cbranch_vccz .LBB0_250
.LBB0_304:
	s_cmp_lg_u64 s[10:11], 0
	v_add_u32_e32 v100, 0x400, v3
	v_add_u32_e32 v99, 0x800, v3
	v_add_u32_e32 v98, 0xc00, v3
	v_add_u32_e32 v97, 0x1000, v3
	v_add_u32_e32 v96, 0x1400, v3
	v_add_u32_e32 v95, 0x1800, v3
	v_add_u32_e32 v32, 0x1c00, v3
	v_add_u32_e32 v11, 0x2000, v3
	v_add_u32_e32 v10, 0x2400, v3
	v_add_u32_e32 v9, 0x2800, v3
	v_add_u32_e32 v8, 0x2c00, v3
	v_add_u32_e32 v7, 0x3000, v3
	v_add_u32_e32 v6, 0x3400, v3
	v_add_u32_e32 v4, 0x3800, v3
	v_add_u32_e32 v5, 0x3c00, v3
	s_cbranch_scc0 .LBB0_336
	v_and_b32_e32 v101, 0x100, v237
	s_waitcnt vmcnt(8)
	ds_bpermute_b32 v102, v101, v94
	ds_bpermute_b32 v103, v101, v94 offset:4
	s_waitcnt lgkmcnt(1)
	v_mul_f32_e32 v102, v28, v102
	s_waitcnt lgkmcnt(0)
	v_mul_f32_e32 v103, v29, v103
	ds_write2_b32 v3, v102, v103 offset1:65
	ds_bpermute_b32 v102, v101, v94 offset:8
	ds_bpermute_b32 v103, v101, v94 offset:12
	s_waitcnt lgkmcnt(1)
	v_mul_f32_e32 v102, v30, v102
	s_waitcnt lgkmcnt(0)
	v_mul_f32_e32 v103, v31, v103
	ds_write2_b32 v3, v102, v103 offset0:130 offset1:195
	ds_bpermute_b32 v102, v101, v94 offset:16
	ds_bpermute_b32 v103, v101, v94 offset:20
	s_waitcnt lgkmcnt(1)
	v_mul_f32_e32 v102, v34, v102
	s_waitcnt lgkmcnt(0)
	v_mul_f32_e32 v103, v35, v103
	ds_write2_b32 v100, v102, v103 offset0:4 offset1:69
	ds_bpermute_b32 v102, v101, v94 offset:24
	ds_bpermute_b32 v103, v101, v94 offset:28
	s_waitcnt lgkmcnt(1)
	v_mul_f32_e32 v102, v36, v102
	s_waitcnt lgkmcnt(0)
	v_mul_f32_e32 v103, v37, v103
	ds_write2_b32 v100, v102, v103 offset0:134 offset1:199
	ds_bpermute_b32 v102, v101, v94 offset:32
	ds_bpermute_b32 v103, v101, v94 offset:36
	s_waitcnt lgkmcnt(1)
	v_mul_f32_e32 v102, v38, v102
	s_waitcnt lgkmcnt(0)
	v_mul_f32_e32 v103, v39, v103
	ds_write2_b32 v99, v102, v103 offset0:8 offset1:73
	ds_bpermute_b32 v102, v101, v94 offset:40
	ds_bpermute_b32 v103, v101, v94 offset:44
	s_waitcnt lgkmcnt(1)
	v_mul_f32_e32 v102, v40, v102
	s_waitcnt lgkmcnt(0)
	v_mul_f32_e32 v103, v41, v103
	ds_write2_b32 v99, v102, v103 offset0:138 offset1:203
	ds_bpermute_b32 v102, v101, v94 offset:48
	ds_bpermute_b32 v103, v101, v94 offset:52
	s_waitcnt lgkmcnt(1)
	v_mul_f32_e32 v102, v42, v102
	s_waitcnt lgkmcnt(0)
	v_mul_f32_e32 v103, v43, v103
	ds_write2_b32 v98, v102, v103 offset0:12 offset1:77
	ds_bpermute_b32 v102, v101, v94 offset:56
	ds_bpermute_b32 v103, v101, v94 offset:60
	s_waitcnt lgkmcnt(1)
	v_mul_f32_e32 v102, v44, v102
	s_waitcnt lgkmcnt(0)
	v_mul_f32_e32 v103, v45, v103
	ds_write2_b32 v98, v102, v103 offset0:142 offset1:207
	ds_bpermute_b32 v102, v101, v94 offset:64
	ds_bpermute_b32 v103, v101, v94 offset:68
	s_waitcnt lgkmcnt(1)
	v_mul_f32_e32 v102, v46, v102
	s_waitcnt lgkmcnt(0)
	v_mul_f32_e32 v103, v47, v103
	ds_write2_b32 v97, v102, v103 offset0:16 offset1:81
	ds_bpermute_b32 v102, v101, v94 offset:72
	ds_bpermute_b32 v103, v101, v94 offset:76
	s_waitcnt lgkmcnt(1)
	v_mul_f32_e32 v102, v48, v102
	s_waitcnt lgkmcnt(0)
	v_mul_f32_e32 v103, v49, v103
	ds_write2_b32 v97, v102, v103 offset0:146 offset1:211
	ds_bpermute_b32 v102, v101, v94 offset:80
	ds_bpermute_b32 v103, v101, v94 offset:84
	s_waitcnt lgkmcnt(1)
	v_mul_f32_e32 v102, v50, v102
	s_waitcnt lgkmcnt(0)
	v_mul_f32_e32 v103, v51, v103
	ds_write2_b32 v96, v102, v103 offset0:20 offset1:85
	ds_bpermute_b32 v102, v101, v94 offset:88
	ds_bpermute_b32 v103, v101, v94 offset:92
	s_waitcnt lgkmcnt(1)
	v_mul_f32_e32 v102, v52, v102
	s_waitcnt lgkmcnt(0)
	v_mul_f32_e32 v103, v53, v103
	ds_write2_b32 v96, v102, v103 offset0:150 offset1:215
	ds_bpermute_b32 v102, v101, v94 offset:96
	ds_bpermute_b32 v103, v101, v94 offset:100
	s_waitcnt lgkmcnt(1)
	v_mul_f32_e32 v102, v54, v102
	s_waitcnt lgkmcnt(0)
	v_mul_f32_e32 v103, v55, v103
	ds_write2_b32 v95, v102, v103 offset0:24 offset1:89
	ds_bpermute_b32 v102, v101, v94 offset:104
	ds_bpermute_b32 v103, v101, v94 offset:108
	s_waitcnt lgkmcnt(1)
	v_mul_f32_e32 v102, v56, v102
	s_waitcnt lgkmcnt(0)
	v_mul_f32_e32 v103, v57, v103
	ds_write2_b32 v95, v102, v103 offset0:154 offset1:219
	ds_bpermute_b32 v102, v101, v94 offset:112
	ds_bpermute_b32 v103, v101, v94 offset:116
	s_waitcnt lgkmcnt(1)
	v_mul_f32_e32 v102, v58, v102
	s_waitcnt lgkmcnt(0)
	v_mul_f32_e32 v103, v59, v103
	ds_write2_b32 v32, v102, v103 offset0:28 offset1:93
	ds_bpermute_b32 v102, v101, v94 offset:120
	ds_bpermute_b32 v103, v101, v94 offset:124
	s_waitcnt lgkmcnt(1)
	v_mul_f32_e32 v102, v60, v102
	s_waitcnt lgkmcnt(0)
;     ...
;             if (cur.ks) {
; #pragma unroll
;                 for (int i = 0; i < 64; ++i) scr[i * 65 + lane] = v[i] * __shfl(kv, i);
	v_mul_f32_e32 v103, v61, v103
	ds_write2_b32 v32, v102, v103 offset0:158 offset1:223
	ds_bpermute_b32 v102, v101, v94 offset:128
	ds_bpermute_b32 v103, v101, v94 offset:132
	s_waitcnt lgkmcnt(1)
	v_mul_f32_e32 v102, v62, v102
	s_waitcnt lgkmcnt(0)
	v_mul_f32_e32 v103, v63, v103
	ds_write2_b32 v11, v102, v103 offset0:32 offset1:97
	ds_bpermute_b32 v102, v101, v94 offset:136
	ds_bpermute_b32 v103, v101, v94 offset:140
	s_waitcnt lgkmcnt(1)
	v_mul_f32_e32 v102, v64, v102
	s_waitcnt lgkmcnt(0)
	v_mul_f32_e32 v103, v65, v103
	ds_write2_b32 v11, v102, v103 offset0:162 offset1:227
	ds_bpermute_b32 v102, v101, v94 offset:144
	ds_bpermute_b32 v103, v101, v94 offset:148
	s_waitcnt lgkmcnt(1)
	v_mul_f32_e32 v102, v66, v102
	s_waitcnt lgkmcnt(0)
	v_mul_f32_e32 v103, v67, v103
	ds_write2_b32 v10, v102, v103 offset0:36 offset1:101
	ds_bpermute_b32 v102, v101, v94 offset:152
	ds_bpermute_b32 v103, v101, v94 offset:156
	s_waitcnt lgkmcnt(1)
	v_mul_f32_e32 v102, v68, v102
	s_waitcnt lgkmcnt(0)
	v_mul_f32_e32 v103, v69, v103
	ds_write2_b32 v10, v102, v103 offset0:166 offset1:231
	ds_bpermute_b32 v102, v101, v94 offset:160
	ds_bpermute_b32 v103, v101, v94 offset:164
	s_waitcnt lgkmcnt(1)
	v_mul_f32_e32 v102, v70, v102
	s_waitcnt lgkmcnt(0)
	v_mul_f32_e32 v103, v71, v103
	ds_write2_b32 v9, v102, v103 offset0:40 offset1:105
	ds_bpermute_b32 v102, v101, v94 offset:168
	ds_bpermute_b32 v103, v101, v94 offset:172
	s_waitcnt lgkmcnt(1)
	v_mul_f32_e32 v102, v72, v102
	s_waitcnt lgkmcnt(0)
	v_mul_f32_e32 v103, v73, v103
	ds_write2_b32 v9, v102, v103 offset0:170 offset1:235
	ds_bpermute_b32 v102, v101, v94 offset:176
	ds_bpermute_b32 v103, v101, v94 offset:180
	s_waitcnt lgkmcnt(1)
	v_mul_f32_e32 v102, v74, v102
	s_waitcnt lgkmcnt(0)
	v_mul_f32_e32 v103, v75, v103
	ds_write2_b32 v8, v102, v103 offset0:44 offset1:109
	ds_bpermute_b32 v102, v101, v94 offset:184
	ds_bpermute_b32 v103, v101, v94 offset:188
	s_waitcnt lgkmcnt(1)
	v_mul_f32_e32 v102, v76, v102
	s_waitcnt lgkmcnt(0)
	v_mul_f32_e32 v103, v77, v103
	ds_write2_b32 v8, v102, v103 offset0:174 offset1:239
	ds_bpermute_b32 v102, v101, v94 offset:192
	ds_bpermute_b32 v103, v101, v94 offset:196
	s_waitcnt lgkmcnt(1)
	v_mul_f32_e32 v102, v78, v102
	s_waitcnt lgkmcnt(0)
	v_mul_f32_e32 v103, v79, v103
	ds_write2_b32 v7, v102, v103 offset0:48 offset1:113
	ds_bpermute_b32 v102, v101, v94 offset:200
	ds_bpermute_b32 v103, v101, v94 offset:204
	s_waitcnt lgkmcnt(1)
	v_mul_f32_e32 v102, v80, v102
	s_waitcnt lgkmcnt(0)
	v_mul_f32_e32 v103, v81, v103
	ds_write2_b32 v7, v102, v103 offset0:178 offset1:243
	ds_bpermute_b32 v102, v101, v94 offset:208
	ds_bpermute_b32 v103, v101, v94 offset:212
	s_waitcnt lgkmcnt(1)
	v_mul_f32_e32 v102, v82, v102
	s_waitcnt lgkmcnt(0)
	v_mul_f32_e32 v103, v83, v103
	ds_write2_b32 v6, v102, v103 offset0:52 offset1:117
	ds_bpermute_b32 v102, v101, v94 offset:216
	ds_bpermute_b32 v103, v101, v94 offset:220
	s_waitcnt lgkmcnt(1)
	v_mul_f32_e32 v102, v84, v102
	s_waitcnt lgkmcnt(0)
	v_mul_f32_e32 v103, v85, v103
	ds_write2_b32 v6, v102, v103 offset0:182 offset1:247
	ds_bpermute_b32 v102, v101, v94 offset:224
	ds_bpermute_b32 v103, v101, v94 offset:228
	s_waitcnt lgkmcnt(1)
	v_mul_f32_e32 v102, v86, v102
	s_waitcnt lgkmcnt(0)
	v_mul_f32_e32 v103, v87, v103
	ds_write2_b32 v4, v102, v103 offset0:56 offset1:121
	ds_bpermute_b32 v102, v101, v94 offset:232
	ds_bpermute_b32 v103, v101, v94 offset:236
	s_waitcnt lgkmcnt(1)
	v_mul_f32_e32 v102, v88, v102
	s_waitcnt lgkmcnt(0)
	v_mul_f32_e32 v103, v89, v103
	ds_write2_b32 v4, v102, v103 offset0:186 offset1:251
	ds_bpermute_b32 v102, v101, v94 offset:240
	ds_bpermute_b32 v103, v101, v94 offset:244
	ds_bpermute_b32 v101, v101, v94 offset:248
	s_waitcnt lgkmcnt(2)
	v_mul_f32_e32 v102, v90, v102
	s_waitcnt lgkmcnt(1)
	v_mul_f32_e32 v103, v91, v103
	s_waitcnt lgkmcnt(0)
	v_mul_f32_e32 v101, v92, v101
	ds_write_b32 v3, v101 offset:16120
	v_or_b32_e32 v101, 0xfc, v237
	ds_bpermute_b32 v94, v101, v94
	ds_write2_b32 v5, v102, v103 offset0:60 offset1:125
	s_waitcnt lgkmcnt(1)
	v_mul_f32_e32 v94, v93, v94
	s_cbranch_execnz .LBB0_307
;     auto decode = [&](int itv) -> TItem {
;         const int it = pre > 0 ? (1 + itv / pre) * I_LAYER + itv % pre : itv;
;         const int layer = it / I_LAYER; int r = it - layer * I_LAYER;
;         unsigned char* wl = ws + WS_W + (size_t)layer * WL_STRIDE;
;         if (r < I_WIN) return TItem{P.w_in + (size_t)layer * D * DIN, (bf16*)(wl + WL_WIN), nullptr, D, DIN, 1, r}; r -= I_WIN;
;         if (r < I_SSDOUT) return TItem{P.ssd_out + (size_t)layer * SSD_INNER * D, (bf16*)(wl + WL_SSDOUT), P.ssd_norm + (size_t)layer * SSD_INNER, SSD_INNER, D, 0, r}; r -= I_SSDOUT;
;         if (r < I_SQ) return TItem{P.sc_out + (size_t)layer * D * D, (bf16*)(wl + WL_SCOUT), nullptr, D, D, 0, r}; r -= I_SQ;
;         if (r < I_SQ) return TItem{P.w_o + (size_t)layer * D * D, (bf16*)(wl + WL_WO), nullptr, D, D, 0, r}; r -= I_SQ;
;         if (r < I_WGU) return TItem{P.w_gate_up + (size_t)layer * D * 2 * DFF, (bf16*)(wl + WL_WGU), nullptr, D, 2 * DFF, 2, r}; r -= I_WGU;
;         if (r < I_WDOWN) return TItem{P.w_down + (size_t)layer * DFF * D, (bf16*)(wl + WL_WDOWN), nullptr, DFF, D, 0, r}; r -= I_WDOWN;
;     ...
;             } else {
; #pragma unroll
;                 for (int i = 0; i < 64; ++i) scr[i * 65 + lane] = v[i];
;             }
;             const int itn = it + nw; const bool hn = itn < it_end; TItem nxt = cur; float kvn = 1.0f;
;             if (hn) { nxt = decode(itn); item_load(nxt, v, kvn, lane); }
.LBB0_306:
	s_waitcnt vmcnt(8)
	v_mov_b32_e32 v94, v93
	ds_write2_b32 v3, v28, v29 offset1:65
	ds_write2_b32 v3, v30, v31 offset0:130 offset1:195
	ds_write2_b32 v100, v34, v35 offset0:4 offset1:69
	ds_write2_b32 v100, v36, v37 offset0:134 offset1:199
	ds_write2_b32 v99, v38, v39 offset0:8 offset1:73
	ds_write2_b32 v99, v40, v41 offset0:138 offset1:203
	ds_write2_b32 v98, v42, v43 offset0:12 offset1:77
	ds_write2_b32 v98, v44, v45 offset0:142 offset1:207
	ds_write2_b32 v97, v46, v47 offset0:16 offset1:81
	ds_write2_b32 v97, v48, v49 offset0:146 offset1:211
	ds_write2_b32 v96, v50, v51 offset0:20 offset1:85
	ds_write2_b32 v96, v52, v53 offset0:150 offset1:215
	ds_write2_b32 v95, v54, v55 offset0:24 offset1:89
	ds_write2_b32 v95, v56, v57 offset0:154 offset1:219
	ds_write2_b32 v32, v58, v59 offset0:28 offset1:93
	ds_write2_b32 v32, v60, v61 offset0:158 offset1:223
	ds_write2_b32 v11, v62, v63 offset0:32 offset1:97
	ds_write2_b32 v11, v64, v65 offset0:162 offset1:227
	ds_write2_b32 v10, v66, v67 offset0:36 offset1:101
	ds_write2_b32 v10, v68, v69 offset0:166 offset1:231
	ds_write2_b32 v9, v70, v71 offset0:40 offset1:105
	ds_write2_b32 v9, v72, v73 offset0:170 offset1:235
	ds_write2_b32 v8, v74, v75 offset0:44 offset1:109
	ds_write2_b32 v8, v76, v77 offset0:174 offset1:239
	ds_write2_b32 v7, v78, v79 offset0:48 offset1:113
	ds_write2_b32 v7, v80, v81 offset0:178 offset1:243
	ds_write2_b32 v6, v82, v83 offset0:52 offset1:117
	ds_write2_b32 v6, v84, v85 offset0:182 offset1:247
	ds_write2_b32 v4, v86, v87 offset0:56 offset1:121
	ds_write2_b32 v4, v88, v89 offset0:186 offset1:251
	ds_write2_b32 v5, v90, v91 offset0:60 offset1:125
	ds_write_b32 v3, v92 offset:16120
.LBB0_307:
	v_readlane_b32 s16, v255, 2
	v_readlane_b32 s17, v255, 3
	v_readlane_b32 s18, v255, 4
	v_readlane_b32 s19, v255, 5
	s_mov_b32 s16, s44
	s_add_i32 s36, s36, s54
	v_writelane_b32 v255, s16, 2
	s_cmp_ge_i32 s36, s33
	s_cselect_b64 s[46:47], -1, 0
	v_writelane_b32 v255, s17, 3
	v_writelane_b32 v255, s18, 4
	s_waitcnt vmcnt(8)
	ds_write_b32 v3, v94 offset:16380
	v_mov_b32_e32 v94, 1.0
	s_and_b64 vcc, exec, s[46:47]
	s_mov_b64 s[14:15], s[6:7]
	s_mov_b32 s41, s37
	v_writelane_b32 v255, s19, 5
	s_mov_b32 s18, s38
	s_mov_b32 s40, s39
	s_cbranch_vccnz .LBB0_339
	s_mul_hi_i32 s9, s36, 0x577f7cc1
	s_lshr_b32 s10, s9, 31
	s_ashr_i32 s9, s9, 13
	s_add_i32 s22, s9, s10
	s_mul_i32 s9, s22, 0xffffa260
	s_add_i32 s24, s9, s36
	s_ashr_i32 s23, s22, 31
	s_mul_i32 s11, s22, 0xbc00000
	s_mul_hi_i32 s10, s22, 0xbc00000
	s_add_u32 s4, s95, s11
	s_addc_u32 s5, s61, s10
	s_cmpk_gt_i32 s24, 0x281f
	s_mov_b64 s[30:31], -1
	s_cbranch_scc0 .LBB0_332
	s_cmpk_gt_u32 s24, 0x301f
	s_mov_b64 s[26:27], -1
	s_cbranch_scc0 .LBB0_330
	s_cmpk_gt_u32 s24, 0x341f
	s_cbranch_scc0 .LBB0_327
	s_cmpk_gt_u32 s24, 0x381f
	s_cbranch_scc0 .LBB0_324
	s_cmpk_gt_u32 s24, 0x4e1f
	s_mov_b64 s[18:19], -1
	s_cbranch_scc0 .LBB0_322
	s_cmpk_gt_u32 s24, 0x591f
	s_cbranch_scc0 .LBB0_319
	s_cmpk_gt_u32 s24, 0x5d1f
	s_cbranch_scc0 .LBB0_316
	v_readlane_b32 s12, v252, 47
	v_readlane_b32 s13, v252, 48
	v_readlane_b32 s14, v252, 49
	v_readlane_b32 s15, v252, 50
	v_readlane_b32 s16, v252, 51
	v_readlane_b32 s17, v252, 52
	v_readlane_b32 s18, v252, 53
	v_readlane_b32 s19, v252, 54
	s_mov_b64 s[12:13], s[16:17]
	s_add_i32 s40, s24, 0xffffa2e0
	s_lshl_b64 s[10:11], s[22:23], 21
	s_mov_b64 s[14:15], s[18:19]
	s_add_u32 s10, s14, s10
	s_addc_u32 s11, s15, s11
	s_add_u32 s14, s4, 0xbb00000
	s_addc_u32 s15, s5, 0
	s_mov_b64 s[18:19], 0

; #define LAS __attribute__((address_space(3)))
; __device__ __forceinline__ unsigned pk2(float lo, float hi) { return pg8::cvt_pk_bf16(lo, hi); }
; __device__ __forceinline__ int rowmap(int mode, int n) {
;     if (mode == 1) return n < 10240 ? n : (n < 10304 ? n + (PC_DT - 10240) : n - 64);
;     if (mode == 2) { const int isup = n >= DFF ? 1 : 0; const int f = n - isup * DFF;
;         return 256 * (f >> 7) + 128 * ((f >> 2) & 1) + 32 * ((f >> 5) & 3) + 16 * isup + 4 * ((f >> 3) & 3) + (f & 3); }
;     return n;
; __device__ __forceinline__ void item_store(const TItem& t, LAS float* scr, int lane) {
;     const int nblk = t.N / 64, kb = t.item / nblk, nb = t.item % nblk, k0 = 64 * kb, n0 = 64 * nb;
;     const int c = lane & 7, nn = lane >> 3;
; #pragma unroll
;     for (int j = 0; j < 8; ++j) { const int n = nn + 8 * j; const LAS float* s = scr + (8 * c) * 65 + n;
;         v4u o; o.x = pk2(s[0 * 65], s[1 * 65]); o.y = pk2(s[2 * 65], s[3 * 65]); o.z = pk2(s[4 * 65], s[5 * 65]); o.w = pk2(s[6 * 65], s[7 * 65]);
;         *(v4u*)(t.WT + (size_t)rowmap(t.mode, n0 + n) * t.K + k0 + 8 * c) = o; }
.LBB0_346:
	s_lshl_b32 s8, s16, 6
	s_waitcnt lgkmcnt(3)
	v_cvt_pk_bf16_f32 v4, v4, v5
	s_waitcnt lgkmcnt(2)
	v_cvt_pk_bf16_f32 v5, v6, v7
	s_waitcnt lgkmcnt(1)
	v_cvt_pk_bf16_f32 v6, v8, v9
	v_mad_u64_u32 v[8:9], s[16:17], v32, s37, 0
	s_waitcnt lgkmcnt(0)
	v_cvt_pk_bf16_f32 v7, v10, v11
	v_ashrrev_i32_e32 v11, 31, v32
	v_mov_b32_e32 v10, v9
	v_mad_u64_u32 v[10:11], s[16:17], v11, s37, v[10:11]
	v_mov_b32_e32 v9, v10
	s_ashr_i32 s9, s8, 31
	v_lshl_add_u64 v[8:9], v[8:9], 1, s[6:7]
	v_lshl_add_u64 v[8:9], s[8:9], 1, v[8:9]
	v_lshlrev_b32_e32 v32, 1, v2
	v_lshl_add_u64 v[8:9], v[8:9], 0, v[32:33]
	v_mov_b64_e32 v[102:103], v[8:9]
	global_store_dwordx4 v[8:9], v[4:7], off
	ds_read2_b32 v[4:5], v14 offset0:8 offset1:73
	ds_read2_b32 v[6:7], v14 offset0:138 offset1:203
	ds_read2_b32 v[8:9], v95 offset0:12 offset1:77
	ds_read2_b32 v[10:11], v95 offset0:142 offset1:207
	s_cmp_eq_u32 s38, 2
	s_cselect_b32 s8, 8, 16
	s_cselect_b32 s9, 40, 16
	s_mul_i32 s8, s8, s37
	s_mul_i32 s9, s9, s37
	s_mov_b32 s101, 0
	s_mov_b32 s100, s8
	ds_read2_b32 v[16:17], v14 offset0:16 offset1:81
	ds_read2_b32 v[18:19], v14 offset0:146 offset1:211
	ds_read2_b32 v[20:21], v95 offset0:20 offset1:85
	ds_read2_b32 v[22:23], v95 offset0:150 offset1:215
	ds_read2_b32 v[96:97], v14 offset0:24 offset1:89
	ds_read2_b32 v[98:99], v14 offset0:154 offset1:219
	ds_read2_b32 v[100:101], v95 offset0:28 offset1:93
	ds_read2_b32 v[24:25], v95 offset0:158 offset1:223
	s_waitcnt lgkmcnt(8)
	v_cvt_pk_bf16_f32 v4, v4, v5
	v_cvt_pk_bf16_f32 v5, v6, v7
	v_cvt_pk_bf16_f32 v6, v8, v9
	v_cvt_pk_bf16_f32 v7, v10, v11
	v_lshl_add_u64 v[102:103], v[102:103], 0, s[100:101]
	global_store_dwordx4 v[102:103], v[4:7], off
	ds_read2_b32 v[4:5], v14 offset0:32 offset1:97
	ds_read2_b32 v[6:7], v14 offset0:162 offset1:227
	ds_read2_b32 v[8:9], v95 offset0:36 offset1:101
	ds_read2_b32 v[10:11], v95 offset0:166 offset1:231
	s_waitcnt lgkmcnt(8)
	v_cvt_pk_bf16_f32 v16, v16, v17
	v_cvt_pk_bf16_f32 v17, v18, v19
	v_cvt_pk_bf16_f32 v18, v20, v21
	v_cvt_pk_bf16_f32 v19, v22, v23
	v_lshl_add_u64 v[102:103], v[102:103], 0, s[100:101]
	global_store_dwordx4 v[102:103], v[16:19], off
	ds_read2_b32 v[16:17], v14 offset0:40 offset1:105
	ds_read2_b32 v[18:19], v14 offset0:170 offset1:235
	ds_read2_b32 v[20:21], v95 offset0:44 offset1:109
	ds_read2_b32 v[22:23], v95 offset0:174 offset1:239
	s_waitcnt lgkmcnt(8)
	v_cvt_pk_bf16_f32 v96, v96, v97
	v_cvt_pk_bf16_f32 v97, v98, v99
	v_cvt_pk_bf16_f32 v98, v100, v101
	v_cvt_pk_bf16_f32 v99, v24, v25
	v_lshl_add_u64 v[102:103], v[102:103], 0, s[100:101]
	global_store_dwordx4 v[102:103], v[96:99], off
	ds_read2_b32 v[96:97], v14 offset0:48 offset1:113
	ds_read2_b32 v[98:99], v14 offset0:178 offset1:243
	ds_read2_b32 v[100:101], v95 offset0:52 offset1:117
	ds_read2_b32 v[24:25], v95 offset0:182 offset1:247
	s_mov_b32 s100, s9
	s_waitcnt lgkmcnt(8)
	v_cvt_pk_bf16_f32 v4, v4, v5
	v_cvt_pk_bf16_f32 v5, v6, v7
	v_cvt_pk_bf16_f32 v6, v8, v9
	v_cvt_pk_bf16_f32 v7, v10, v11
	v_lshl_add_u64 v[102:103], v[102:103], 0, s[100:101]
	global_store_dwordx4 v[102:103], v[4:7], off
	s_mov_b32 s100, s8
	ds_read2_b32 v[4:5], v14 offset0:56 offset1:121
	ds_read2_b32 v[6:7], v14 offset0:186 offset1:251
	ds_read2_b32 v[8:9], v95 offset0:60 offset1:125
	ds_read2_b32 v[10:11], v95 offset0:190 offset1:255
	s_waitcnt lgkmcnt(8)
	v_cvt_pk_bf16_f32 v16, v16, v17
	v_cvt_pk_bf16_f32 v17, v18, v19
	v_cvt_pk_bf16_f32 v18, v20, v21
	v_cvt_pk_bf16_f32 v19, v22, v23
	v_lshl_add_u64 v[102:103], v[102:103], 0, s[100:101]
	global_store_dwordx4 v[102:103], v[16:19], off
	s_waitcnt lgkmcnt(4)
	v_cvt_pk_bf16_f32 v96, v96, v97
	v_cvt_pk_bf16_f32 v97, v98, v99
	v_cvt_pk_bf16_f32 v98, v100, v101
	v_cvt_pk_bf16_f32 v99, v24, v25
	v_lshl_add_u64 v[102:103], v[102:103], 0, s[100:101]
	global_store_dwordx4 v[102:103], v[96:99], off
	s_waitcnt lgkmcnt(0)
	v_cvt_pk_bf16_f32 v4, v4, v5
	v_cvt_pk_bf16_f32 v5, v6, v7
	v_cvt_pk_bf16_f32 v6, v8, v9
	v_cvt_pk_bf16_f32 v7, v10, v11
	v_lshl_add_u64 v[102:103], v[102:103], 0, s[100:101]
	global_store_dwordx4 v[102:103], v[4:7], off
	s_branch .Lconv_tail_g1

; #define GPROBE_BEGIN(id) do { if (((PROBE_GEMM_SEL >> (id)) & 1) && blockIdx.x == 0 && tid_in < 64 && g.N == 20480) { volatile PG8_LAS unsigned long long* PW_ = (volatile PG8_LAS unsigned long long*)(lds + 163840 - 512 + 64); PW_[0] = __builtin_amdgcn_s_memrealtime(); } } while (0)
; #define GPROBE_END(id) do { if (((PROBE_GEMM_SEL >> (id)) & 1) && blockIdx.x == 0 && tid_in < 64 && g.N == 20480) { volatile PG8_LAS unsigned long long* PW_ = (volatile PG8_LAS unsigned long long*)(lds + 163840 - 512 + 64); PW_[1] += __builtin_amdgcn_s_memrealtime() - PW_[0]; } } while (0)
; #define PG8_BAR __builtin_amdgcn_s_barrier()
; template <class Epi, class Sched, bool ALIGN_EPI = false, bool SP2 = false, bool KHOOK = false>
; __device__ __forceinline__ void gemm_phase(PG8_LAS unsigned char* lds, const Gemm g, const Sched& S, const Epi& E, const int tid_in) {
;     ...
;         const char* nA = has_next ? (const char*)g.A + (size_t)nxt.pm * tstep + (size_t)nxt.pn * ksl : cA; const char* nB = has_next ? (const char*)g.Bt + (size_t)nxt.pn * bts + (size_t)nxt.pn * ksl + (gdv ? (size_t)(nxt.pm / gdv) * gst : 0) : cB;
;         GPROBE_END(2); GPROBE_BEGIN(1);
;         for (int t = 0; t < nt; t += 2) {
;             const bool last = (t == nt - 2);
;             const char* a1 = cA + (size_t)(t + 1) * kstep;
;             const char* a2 = last ? nA : cA + (size_t)(t + 2) * kstep; const char* b2 = last ? nB : cB + (size_t)(t + 2) * kstep;
;             const char* a3 = a2 + kstep; const char* b3 = b2 + kstep;
;             if (last && has_next) S.a_ready(nxt);
;             if constexpr (SP2) {
;             PG8_LDB(B0, 0, 0); PG8_LDB(B1, 0, 1); PG8_SCHED; PG8_LDA(At, 0, 0); PG8_STAGE(PG8_SA(1, 1), a1 + hstep, voffA);
;             PG8_WAIT_V(8); PG8_WAIT_L(0); PG8_BAR; PG8_MMA(0, 0, At, B0); PG8_MMA(0, 1, At, B1); PG8_BAR; PG8_SCHED;
;             PG8_LDA(At, 0, 1); PG8_STAGE(PG8_SB(0, 0), b2, voffB); PG8_STAGE(PG8_SB(0, 1), b2 + hstep, voffB); PG8_STAGE(PG8_SA(0, 0), a2, voffA);
;             PG8_WAIT_V(8); PG8_WAIT_L(0); PG8_BAR; PG8_MMA(1, 0, At, B0); PG8_MMA(1, 1, At, B1); PG8_BAR; PG8_SCHED;
;     ...
; #pragma unroll
;         for (int a = 0; a < 2; ++a)
; #pragma unroll
;             for (int b = 0; b < 2; ++b)
; #pragma unroll
;                 for (int m = 0; m < 4; ++m)
; #pragma unroll
;                     for (int n = 0; n < 2; ++n) acc[a][b][m][n] = (f32x4){0.f, 0.f, 0.f, 0.f};
.LBB0_866:
	s_ashr_i32 s9, s8, 31
	s_lshl_b64 s[12:13], s[8:9], 20
	s_add_u32 s12, s55, s12
	v_readlane_b32 s7, v253, 61
	s_addc_u32 s13, s7, s13
	s_and_b64 s[14:15], s[10:11], exec
	s_cselect_b32 s9, s13, s17
	s_cselect_b32 s39, s12, s16
	s_ashr_i32 s7, s6, 31
	s_lshl_b64 s[14:15], s[6:7], 20
	s_add_u32 s14, s2, s14
	s_addc_u32 s15, s18, s15
	s_and_b64 s[26:27], s[10:11], exec
	s_cselect_b32 s7, s15, s23
	s_cselect_b32 s40, s14, s22
	s_add_u32 s16, s16, 0x80080
	s_addc_u32 s17, s17, 0
	s_add_u32 s41, s22, 0x100
	s_addc_u32 s42, s23, 0
	s_mov_b32 s44, -2
	s_add_u32 s22, s16, 0xfff80080
	s_addc_u32 s23, s17, -1
	s_add_i32 s45, 0, 0x10000
	s_cmp_eq_u32 s44, 28
	s_cselect_b32 s27, s9, s23
	s_cselect_b32 s26, s39, s22
	s_cselect_b32 s23, s7, s42
	s_cselect_b32 s22, s40, s41
	s_add_i32 s48, 0, 0x14000
	v_add_u32_e32 v130, s45, v247
	v_add_u32_e32 v154, s48, v247
	ds_read_b128 v[106:109], v130
	ds_read_b128 v[110:113], v130 offset:1024
	ds_read_b128 v[122:125], v130 offset:2048
	ds_read_b128 v[130:133], v130 offset:3072
	ds_read_b128 v[134:137], v154
	ds_read_b128 v[138:141], v154 offset:1024
	ds_read_b128 v[150:153], v154 offset:2048
	ds_read_b128 v[154:157], v154 offset:3072
	v_lshl_add_u64 v[198:199], s[16:17], 0, v[208:209]
	s_add_i32 m0, s20, 0xc000
	ds_read_b128 v[158:161], v249
	ds_read_b128 v[162:165], v249 offset:1024
	ds_read_b128 v[170:173], v249 offset:2048
	ds_read_b128 v[174:177], v249 offset:3072
	ds_read_b128 v[178:181], v249 offset:4096
	ds_read_b128 v[182:185], v249 offset:5120
	ds_read_b128 v[186:189], v249 offset:6144
	ds_read_b128 v[190:193], v249 offset:7168
	global_load_lds_dwordx4 v[198:199], off
	v_lshl_add_u64 v[198:199], s[16:17], 0, v[210:211]
	s_add_i32 m0, s20, 0xe000
	s_nop 0
	global_load_lds_dwordx4 v[198:199], off
	s_waitcnt vmcnt(8)
	s_waitcnt lgkmcnt(0)
	s_barrier
	s_setprio 1
	s_waitcnt lgkmcnt(0)
	v_mfma_f32_16x16x32_bf16 v[166:169], v[106:109], v[158:161], 0
	v_mfma_f32_16x16x32_bf16 v[146:149], v[122:125], v[158:161], 0
	v_mfma_f32_16x16x32_bf16 v[118:121], v[106:109], v[170:173], 0
	v_mfma_f32_16x16x32_bf16 v[114:117], v[122:125], v[170:173], 0
	v_mfma_f32_16x16x32_bf16 v[94:97], v[106:109], v[178:181], 0
	v_mfma_f32_16x16x32_bf16 v[90:93], v[122:125], v[178:181], 0
	v_mfma_f32_16x16x32_bf16 v[78:81], v[106:109], v[186:189], 0
	v_mfma_f32_16x16x32_bf16 v[74:77], v[122:125], v[186:189], 0
	v_mfma_f32_16x16x32_bf16 v[166:169], v[110:113], v[162:165], v[166:169]
	v_mfma_f32_16x16x32_bf16 v[146:149], v[130:133], v[162:165], v[146:149]
	v_mfma_f32_16x16x32_bf16 v[118:121], v[110:113], v[174:177], v[118:121]
	v_mfma_f32_16x16x32_bf16 v[114:117], v[130:133], v[174:177], v[114:117]
	v_mfma_f32_16x16x32_bf16 v[94:97], v[110:113], v[182:185], v[94:97]
	v_mfma_f32_16x16x32_bf16 v[90:93], v[130:133], v[182:185], v[90:93]
	v_mfma_f32_16x16x32_bf16 v[78:81], v[110:113], v[190:193], v[78:81]
	v_mfma_f32_16x16x32_bf16 v[74:77], v[130:133], v[190:193], v[74:77]
	s_setprio 0
	s_setprio 1
	v_mfma_f32_16x16x32_bf16 v[142:145], v[134:137], v[158:161], 0
	v_mfma_f32_16x16x32_bf16 v[126:129], v[150:153], v[158:161], 0
	v_mfma_f32_16x16x32_bf16 v[102:105], v[134:137], v[170:173], 0
	v_mfma_f32_16x16x32_bf16 v[98:101], v[150:153], v[170:173], 0
	v_mfma_f32_16x16x32_bf16 v[86:89], v[134:137], v[178:181], 0
	v_mfma_f32_16x16x32_bf16 v[82:85], v[150:153], v[178:181], 0
	v_mfma_f32_16x16x32_bf16 v[70:73], v[134:137], v[186:189], 0
	v_mfma_f32_16x16x32_bf16 v[66:69], v[150:153], v[186:189], 0
	v_mfma_f32_16x16x32_bf16 v[142:145], v[138:141], v[162:165], v[142:145]
	v_mfma_f32_16x16x32_bf16 v[126:129], v[154:157], v[162:165], v[126:129]
	v_mfma_f32_16x16x32_bf16 v[102:105], v[138:141], v[174:177], v[102:105]
	v_mfma_f32_16x16x32_bf16 v[98:101], v[154:157], v[174:177], v[98:101]
	v_mfma_f32_16x16x32_bf16 v[86:89], v[138:141], v[182:185], v[86:89]
	v_mfma_f32_16x16x32_bf16 v[82:85], v[154:157], v[182:185], v[82:85]
	v_mfma_f32_16x16x32_bf16 v[70:73], v[138:141], v[190:193], v[70:73]
	v_mfma_f32_16x16x32_bf16 v[66:69], v[154:157], v[190:193], v[66:69]
	s_setprio 0
	s_barrier
	s_add_i32 s45, s45, s19
	v_lshl_add_u64 v[198:199], s[22:23], 0, v[32:33]
	s_mov_b32 m0, s45
	ds_read_b128 v[158:161], v249 offset:16384
	ds_read_b128 v[162:165], v249 offset:17408
	ds_read_b128 v[170:173], v249 offset:18432
	ds_read_b128 v[174:177], v249 offset:19456
	ds_read_b128 v[178:181], v249 offset:20480
	ds_read_b128 v[182:185], v249 offset:21504
	ds_read_b128 v[186:189], v249 offset:22528
	ds_read_b128 v[190:193], v249 offset:23552
	global_load_lds_dwordx4 v[198:199], off
	s_add_i32 m0, s45, 0x2000
	s_add_u32 s46, s22, 0x80000
	v_lshl_add_u64 v[200:201], s[22:23], 0, v[202:203]
	s_addc_u32 s47, s23, 0
	s_add_i32 s45, s48, s19
	global_load_lds_dwordx4 v[200:201], off
	v_lshl_add_u64 v[212:213], s[46:47], 0, v[32:33]
	s_mov_b32 m0, s45
	v_lshl_add_u64 v[214:215], s[26:27], 0, v[204:205]
	global_load_lds_dwordx4 v[212:213], off
	v_lshl_add_u64 v[212:213], s[46:47], 0, v[202:203]
	s_add_i32 m0, s45, 0x2000
	s_nop 0
	global_load_lds_dwordx4 v[212:213], off
	v_lshl_add_u64 v[212:213], s[26:27], 0, v[206:207]
	s_mov_b32 m0, s20
	s_nop 0
	global_load_lds_dwordx4 v[212:213], off
	s_mov_b32 m0, s30
	s_nop 0
	global_load_lds_dwordx4 v[214:215], off
	s_waitcnt vmcnt(8)
	s_waitcnt lgkmcnt(0)
	s_barrier
; #define PG8_STAGE(bufoff, gbase, voff) do { _Pragma("unroll") for (int _i = 0; _i < 2; ++_i) \
;         __builtin_amdgcn_global_load_lds((const unsigned*)((const char*)(gbase) + (voff)[_i]), (PG8_LAS unsigned*)(lds + (bufoff) + ldsw + _i * 8192), 16, 0, 0); } while (0)
; #define PG8_LDA(dst, b, h) do { _Pragma("unroll") for (int m = 0; m < 4; ++m) _Pragma("unroll") for (int k = 0; k < 2; ++k) dst[m][k] = *(const PG8_LAS bf16x8*)(lds + PG8_SA(b, h) + aoff + m * 2048 + k * 1024); } while (0)
; #define PG8_LDB(dst, b, h) do { _Pragma("unroll") for (int n = 0; n < 2; ++n) _Pragma("unroll") for (int k = 0; k < 2; ++k) dst[n][k] = *(const PG8_LAS bf16x8*)(lds + PG8_SB(b, h) + boff + n * 2048 + k * 1024); } while (0)
; #define PG8_MMA(ai, bj, At, Bt) do { __builtin_amdgcn_s_setprio(1); _Pragma("unroll") for (int m = 0; m < 4; ++m) _Pragma("unroll") for (int n = 0; n < 2; ++n) _Pragma("unroll") for (int k = 0; k < 2; ++k) \
;         acc[ai][bj][m][n] = __builtin_amdgcn_mfma_f32_16x16x32_bf16(Bt[n][k], At[m][k], acc[ai][bj][m][n], 0, 0, 0); __builtin_amdgcn_s_setprio(0); } while (0)
; #define PG8_WAIT_V(n) asm volatile("s_waitcnt vmcnt(" #n ")" ::: "memory")
; #define PG8_WAIT_L(n) asm volatile("s_waitcnt lgkmcnt(" #n ")" ::: "memory")
; #define PG8_BAR __builtin_amdgcn_s_barrier()
; #define PG8_SCHED __builtin_amdgcn_sched_barrier(0)
; template <class Epi, class Sched, bool ALIGN_EPI = false, bool SP2 = false, bool KHOOK = false>
; __device__ __forceinline__ void gemm_phase(PG8_LAS unsigned char* lds, const Gemm g, const Sched& S, const Epi& E, const int tid_in) {
;     ...
;             PG8_WAIT_V(8); PG8_WAIT_L(0); PG8_BAR; PG8_MMA(1, 0, At, B0); PG8_MMA(1, 1, At, B1); PG8_BAR; PG8_SCHED;
;             PG8_LDB(B0, 1, 0); PG8_LDB(B1, 1, 1); PG8_SCHED; PG8_LDA(At, 1, 0); PG8_STAGE(PG8_SA(0, 1), a2 + hstep, voffA);
;             PG8_WAIT_V(8); PG8_WAIT_L(0); PG8_BAR; PG8_MMA(0, 0, At, B0); PG8_MMA(0, 1, At, B1); PG8_BAR; PG8_SCHED;
	s_setprio 1
	s_waitcnt lgkmcnt(0)
	v_mfma_f32_16x16x32_bf16 v[62:65], v[106:109], v[158:161], 0
	v_mfma_f32_16x16x32_bf16 v[58:61], v[122:125], v[158:161], 0
	v_mfma_f32_16x16x32_bf16 v[46:49], v[106:109], v[170:173], 0
	v_mfma_f32_16x16x32_bf16 v[42:45], v[122:125], v[170:173], 0
	v_mfma_f32_16x16x32_bf16 v[28:31], v[106:109], v[178:181], 0
	v_mfma_f32_16x16x32_bf16 v[24:27], v[122:125], v[178:181], 0
	v_mfma_f32_16x16x32_bf16 v[12:15], v[106:109], v[186:189], 0
	v_mfma_f32_16x16x32_bf16 v[8:11], v[122:125], v[186:189], 0
	v_mfma_f32_16x16x32_bf16 v[62:65], v[110:113], v[162:165], v[62:65]
	v_mfma_f32_16x16x32_bf16 v[58:61], v[130:133], v[162:165], v[58:61]
	v_mfma_f32_16x16x32_bf16 v[46:49], v[110:113], v[174:177], v[46:49]
	v_mfma_f32_16x16x32_bf16 v[42:45], v[130:133], v[174:177], v[42:45]
	v_mfma_f32_16x16x32_bf16 v[28:31], v[110:113], v[182:185], v[28:31]
	v_mfma_f32_16x16x32_bf16 v[24:27], v[130:133], v[182:185], v[24:27]
	v_mfma_f32_16x16x32_bf16 v[12:15], v[110:113], v[190:193], v[12:15]
	v_mfma_f32_16x16x32_bf16 v[8:11], v[130:133], v[190:193], v[8:11]
	s_setprio 0
	s_setprio 1
	v_mfma_f32_16x16x32_bf16 v[54:57], v[134:137], v[158:161], 0
	v_mfma_f32_16x16x32_bf16 v[50:53], v[150:153], v[158:161], 0
	v_mfma_f32_16x16x32_bf16 v[38:41], v[134:137], v[170:173], 0
	v_mfma_f32_16x16x32_bf16 v[34:37], v[150:153], v[170:173], 0
	v_mfma_f32_16x16x32_bf16 v[20:23], v[134:137], v[178:181], 0
	v_mfma_f32_16x16x32_bf16 v[16:19], v[150:153], v[178:181], 0
	v_mfma_f32_16x16x32_bf16 v[4:7], v[134:137], v[186:189], 0
	v_mfma_f32_16x16x32_bf16 v[0:3], v[150:153], v[186:189], 0
	v_mfma_f32_16x16x32_bf16 v[54:57], v[138:141], v[162:165], v[54:57]
	v_mfma_f32_16x16x32_bf16 v[50:53], v[154:157], v[162:165], v[50:53]
	v_mfma_f32_16x16x32_bf16 v[38:41], v[138:141], v[174:177], v[38:41]
	v_mfma_f32_16x16x32_bf16 v[34:37], v[154:157], v[174:177], v[34:37]
	v_mfma_f32_16x16x32_bf16 v[20:23], v[138:141], v[182:185], v[20:23]
	v_mfma_f32_16x16x32_bf16 v[16:19], v[154:157], v[182:185], v[16:19]
	v_mfma_f32_16x16x32_bf16 v[4:7], v[138:141], v[190:193], v[4:7]
	v_mfma_f32_16x16x32_bf16 v[0:3], v[154:157], v[190:193], v[0:3]
	s_setprio 0
	s_barrier
	s_add_i32 s45, 0, 0x18000
	s_add_i32 s46, 0, 0x1c000
	v_add_u32_e32 v130, s45, v247
	v_add_u32_e32 v154, s46, v247
	ds_read_b128 v[106:109], v130
	ds_read_b128 v[110:113], v130 offset:1024
	ds_read_b128 v[122:125], v130 offset:2048
	ds_read_b128 v[130:133], v130 offset:3072
	ds_read_b128 v[134:137], v154
	ds_read_b128 v[138:141], v154 offset:1024
	ds_read_b128 v[150:153], v154 offset:2048
	ds_read_b128 v[154:157], v154 offset:3072
	s_add_u32 s26, s26, 0x80000
	s_addc_u32 s27, s27, 0
	s_mov_b32 m0, s31
	v_lshl_add_u64 v[216:217], s[26:27], 0, v[206:207]
	ds_read_b128 v[158:161], v249 offset:32768
	ds_read_b128 v[162:165], v249 offset:33792
	ds_read_b128 v[170:173], v249 offset:34816
	ds_read_b128 v[174:177], v249 offset:35840
	ds_read_b128 v[178:181], v249 offset:36864
	ds_read_b128 v[182:185], v249 offset:37888
	ds_read_b128 v[186:189], v249 offset:38912
	ds_read_b128 v[190:193], v249 offset:39936
	global_load_lds_dwordx4 v[216:217], off
	v_lshl_add_u64 v[216:217], s[26:27], 0, v[204:205]
	s_mov_b32 m0, s33
	s_nop 0
	global_load_lds_dwordx4 v[216:217], off
	s_waitcnt vmcnt(8)
	s_waitcnt lgkmcnt(0)
	s_barrier
	s_setprio 1
	s_waitcnt lgkmcnt(0)
	v_mfma_f32_16x16x32_bf16 v[166:169], v[106:109], v[158:161], v[166:169]
	v_mfma_f32_16x16x32_bf16 v[146:149], v[122:125], v[158:161], v[146:149]
	v_mfma_f32_16x16x32_bf16 v[118:121], v[106:109], v[170:173], v[118:121]
	v_mfma_f32_16x16x32_bf16 v[114:117], v[122:125], v[170:173], v[114:117]
	v_mfma_f32_16x16x32_bf16 v[94:97], v[106:109], v[178:181], v[94:97]
	v_mfma_f32_16x16x32_bf16 v[90:93], v[122:125], v[178:181], v[90:93]
	v_mfma_f32_16x16x32_bf16 v[78:81], v[106:109], v[186:189], v[78:81]
	v_mfma_f32_16x16x32_bf16 v[74:77], v[122:125], v[186:189], v[74:77]
	v_mfma_f32_16x16x32_bf16 v[166:169], v[110:113], v[162:165], v[166:169]
	v_mfma_f32_16x16x32_bf16 v[146:149], v[130:133], v[162:165], v[146:149]
	v_mfma_f32_16x16x32_bf16 v[118:121], v[110:113], v[174:177], v[118:121]
	v_mfma_f32_16x16x32_bf16 v[114:117], v[130:133], v[174:177], v[114:117]
	v_mfma_f32_16x16x32_bf16 v[94:97], v[110:113], v[182:185], v[94:97]
	v_mfma_f32_16x16x32_bf16 v[90:93], v[130:133], v[182:185], v[90:93]
	v_mfma_f32_16x16x32_bf16 v[78:81], v[110:113], v[190:193], v[78:81]
	v_mfma_f32_16x16x32_bf16 v[74:77], v[130:133], v[190:193], v[74:77]
	s_setprio 0
	s_setprio 1
	v_mfma_f32_16x16x32_bf16 v[142:145], v[134:137], v[158:161], v[142:145]
	v_mfma_f32_16x16x32_bf16 v[126:129], v[150:153], v[158:161], v[126:129]
	v_mfma_f32_16x16x32_bf16 v[102:105], v[134:137], v[170:173], v[102:105]
	v_mfma_f32_16x16x32_bf16 v[98:101], v[150:153], v[170:173], v[98:101]
	v_mfma_f32_16x16x32_bf16 v[86:89], v[134:137], v[178:181], v[86:89]
	v_mfma_f32_16x16x32_bf16 v[82:85], v[150:153], v[178:181], v[82:85]
	v_mfma_f32_16x16x32_bf16 v[70:73], v[134:137], v[186:189], v[70:73]
	v_mfma_f32_16x16x32_bf16 v[66:69], v[150:153], v[186:189], v[66:69]
	v_mfma_f32_16x16x32_bf16 v[142:145], v[138:141], v[162:165], v[142:145]
	v_mfma_f32_16x16x32_bf16 v[126:129], v[154:157], v[162:165], v[126:129]
	v_mfma_f32_16x16x32_bf16 v[102:105], v[138:141], v[174:177], v[102:105]
	v_mfma_f32_16x16x32_bf16 v[98:101], v[154:157], v[174:177], v[98:101]
	v_mfma_f32_16x16x32_bf16 v[86:89], v[138:141], v[182:185], v[86:89]
	v_mfma_f32_16x16x32_bf16 v[82:85], v[154:157], v[182:185], v[82:85]
	v_mfma_f32_16x16x32_bf16 v[70:73], v[138:141], v[190:193], v[70:73]
	v_mfma_f32_16x16x32_bf16 v[66:69], v[154:157], v[190:193], v[66:69]
	s_setprio 0
	s_barrier
; #define PG8_STAGE(bufoff, gbase, voff) do { _Pragma("unroll") for (int _i = 0; _i < 2; ++_i) \
;         __builtin_amdgcn_global_load_lds((const unsigned*)((const char*)(gbase) + (voff)[_i]), (PG8_LAS unsigned*)(lds + (bufoff) + ldsw + _i * 8192), 16, 0, 0); } while (0)
; #define PG8_LDA(dst, b, h) do { _Pragma("unroll") for (int m = 0; m < 4; ++m) _Pragma("unroll") for (int k = 0; k < 2; ++k) dst[m][k] = *(const PG8_LAS bf16x8*)(lds + PG8_SA(b, h) + aoff + m * 2048 + k * 1024); } while (0)
; #define PG8_MMA(ai, bj, At, Bt) do { __builtin_amdgcn_s_setprio(1); _Pragma("unroll") for (int m = 0; m < 4; ++m) _Pragma("unroll") for (int n = 0; n < 2; ++n) _Pragma("unroll") for (int k = 0; k < 2; ++k) \
;         acc[ai][bj][m][n] = __builtin_amdgcn_mfma_f32_16x16x32_bf16(Bt[n][k], At[m][k], acc[ai][bj][m][n], 0, 0, 0); __builtin_amdgcn_s_setprio(0); } while (0)
; #define PG8_WAIT_V(n) asm volatile("s_waitcnt vmcnt(" #n ")" ::: "memory")
; #define PG8_WAIT_L(n) asm volatile("s_waitcnt lgkmcnt(" #n ")" ::: "memory")
; #define PG8_BAR __builtin_amdgcn_s_barrier()
; #define PG8_SCHED __builtin_amdgcn_sched_barrier(0)
; template <class Epi, class Sched, bool ALIGN_EPI = false, bool SP2 = false, bool KHOOK = false>
; __device__ __forceinline__ void gemm_phase(PG8_LAS unsigned char* lds, const Gemm g, const Sched& S, const Epi& E, const int tid_in) {
;     ...
;         for (int t = 0; t < nt; t += 2) {
;             const bool last = (t == nt - 2);
;             const char* a1 = cA + (size_t)(t + 1) * kstep;
;             const char* a2 = last ? nA : cA + (size_t)(t + 2) * kstep; const char* b2 = last ? nB : cB + (size_t)(t + 2) * kstep;
;     ...
;             PG8_LDA(At, 1, 1); PG8_STAGE(PG8_SB(1, 0), b3, voffB); PG8_STAGE(PG8_SB(1, 1), b3 + hstep, voffB); PG8_STAGE(PG8_SA(1, 0), a3, voffA);
;             PG8_WAIT_V(8); PG8_WAIT_L(0); PG8_BAR; PG8_MMA(1, 0, At, B0); PG8_MMA(1, 1, At, B1); PG8_BAR; PG8_SCHED;
	s_add_i32 s26, s45, s19
	v_lshl_add_u64 v[198:199], v[198:199], 0, s[90:91]
	s_mov_b32 m0, s26
	ds_read_b128 v[158:161], v249 offset:49152
	ds_read_b128 v[162:165], v249 offset:50176
	ds_read_b128 v[170:173], v249 offset:51200
	ds_read_b128 v[174:177], v249 offset:52224
	ds_read_b128 v[178:181], v249 offset:53248
	ds_read_b128 v[182:185], v249 offset:54272
	ds_read_b128 v[186:189], v249 offset:55296
	ds_read_b128 v[190:193], v249 offset:56320
	global_load_lds_dwordx4 v[198:199], off
	s_add_i32 m0, s26, 0x2000
	s_add_u32 s22, s22, 0x80080
	v_lshl_add_u64 v[198:199], v[200:201], 0, s[90:91]
	s_addc_u32 s23, s23, 0
	s_add_i32 s26, s46, s19
	global_load_lds_dwordx4 v[198:199], off
	v_lshl_add_u64 v[198:199], s[22:23], 0, v[32:33]
	s_mov_b32 m0, s26
	s_nop 0
	global_load_lds_dwordx4 v[198:199], off
	v_lshl_add_u64 v[198:199], s[22:23], 0, v[202:203]
	s_add_i32 m0, s26, 0x2000
	s_nop 0
	global_load_lds_dwordx4 v[198:199], off
	v_lshl_add_u64 v[198:199], v[212:213], 0, s[90:91]
	s_mov_b32 m0, s36
	s_nop 0
	global_load_lds_dwordx4 v[198:199], off
	v_lshl_add_u64 v[198:199], v[214:215], 0, s[90:91]
	s_mov_b32 m0, s37
	s_nop 0
	global_load_lds_dwordx4 v[198:199], off
	s_waitcnt vmcnt(8)
	s_waitcnt lgkmcnt(0)
	s_barrier
	s_setprio 1
	s_waitcnt lgkmcnt(0)
	v_mfma_f32_16x16x32_bf16 v[62:65], v[106:109], v[158:161], v[62:65]
	v_mfma_f32_16x16x32_bf16 v[58:61], v[122:125], v[158:161], v[58:61]
	v_mfma_f32_16x16x32_bf16 v[46:49], v[106:109], v[170:173], v[46:49]
	v_mfma_f32_16x16x32_bf16 v[42:45], v[122:125], v[170:173], v[42:45]
	v_mfma_f32_16x16x32_bf16 v[28:31], v[106:109], v[178:181], v[28:31]
	v_mfma_f32_16x16x32_bf16 v[24:27], v[122:125], v[178:181], v[24:27]
	v_mfma_f32_16x16x32_bf16 v[12:15], v[106:109], v[186:189], v[12:15]
	v_mfma_f32_16x16x32_bf16 v[8:11], v[122:125], v[186:189], v[8:11]
	v_mfma_f32_16x16x32_bf16 v[62:65], v[110:113], v[162:165], v[62:65]
	v_mfma_f32_16x16x32_bf16 v[58:61], v[130:133], v[162:165], v[58:61]
	v_mfma_f32_16x16x32_bf16 v[46:49], v[110:113], v[174:177], v[46:49]
	v_mfma_f32_16x16x32_bf16 v[42:45], v[130:133], v[174:177], v[42:45]
	v_mfma_f32_16x16x32_bf16 v[28:31], v[110:113], v[182:185], v[28:31]
	v_mfma_f32_16x16x32_bf16 v[24:27], v[130:133], v[182:185], v[24:27]
	v_mfma_f32_16x16x32_bf16 v[12:15], v[110:113], v[190:193], v[12:15]
	v_mfma_f32_16x16x32_bf16 v[8:11], v[130:133], v[190:193], v[8:11]
	s_setprio 0
	s_setprio 1
	v_mfma_f32_16x16x32_bf16 v[54:57], v[134:137], v[158:161], v[54:57]
	v_mfma_f32_16x16x32_bf16 v[50:53], v[150:153], v[158:161], v[50:53]
	v_mfma_f32_16x16x32_bf16 v[38:41], v[134:137], v[170:173], v[38:41]
	v_mfma_f32_16x16x32_bf16 v[34:37], v[150:153], v[170:173], v[34:37]
	v_mfma_f32_16x16x32_bf16 v[20:23], v[134:137], v[178:181], v[20:23]
	v_mfma_f32_16x16x32_bf16 v[16:19], v[150:153], v[178:181], v[16:19]
	v_mfma_f32_16x16x32_bf16 v[4:7], v[134:137], v[186:189], v[4:7]
	v_mfma_f32_16x16x32_bf16 v[0:3], v[150:153], v[186:189], v[0:3]
	v_mfma_f32_16x16x32_bf16 v[54:57], v[138:141], v[162:165], v[54:57]
	v_mfma_f32_16x16x32_bf16 v[50:53], v[154:157], v[162:165], v[50:53]
	v_mfma_f32_16x16x32_bf16 v[38:41], v[138:141], v[174:177], v[38:41]
	v_mfma_f32_16x16x32_bf16 v[34:37], v[154:157], v[174:177], v[34:37]
	v_mfma_f32_16x16x32_bf16 v[20:23], v[138:141], v[182:185], v[20:23]
	v_mfma_f32_16x16x32_bf16 v[16:19], v[154:157], v[182:185], v[16:19]
	v_mfma_f32_16x16x32_bf16 v[4:7], v[138:141], v[190:193], v[4:7]
	v_mfma_f32_16x16x32_bf16 v[0:3], v[154:157], v[190:193], v[0:3]
	s_setprio 0
	s_barrier
	s_add_i32 s44, s44, 2
	s_add_u32 s16, s16, 0x100
	s_addc_u32 s17, s17, 0
	s_add_u32 s41, s41, 0x100
	s_addc_u32 s42, s42, 0
	s_cmp_gt_u32 s44, 29

; #define GPROBE_BEGIN(id) do { if (((PROBE_GEMM_SEL >> (id)) & 1) && blockIdx.x == 0 && tid_in < 64 && g.N == 20480) { volatile PG8_LAS unsigned long long* PW_ = (volatile PG8_LAS unsigned long long*)(lds + 163840 - 512 + 64); PW_[0] = __builtin_amdgcn_s_memrealtime(); } } while (0)
; #define GPROBE_END(id) do { if (((PROBE_GEMM_SEL >> (id)) & 1) && blockIdx.x == 0 && tid_in < 64 && g.N == 20480) { volatile PG8_LAS unsigned long long* PW_ = (volatile PG8_LAS unsigned long long*)(lds + 163840 - 512 + 64); PW_[1] += __builtin_amdgcn_s_memrealtime() - PW_[0]; } } while (0)
; #define PG8_BAR __builtin_amdgcn_s_barrier()
; template <class Epi, class Sched, bool ALIGN_EPI = false, bool SP2 = false, bool KHOOK = false>
; __device__ __forceinline__ void gemm_phase(PG8_LAS unsigned char* lds, const Gemm g, const Sched& S, const Epi& E, const int tid_in) {
;     ...
;         const char* nA = has_next ? (const char*)g.A + (size_t)nxt.pm * tstep + (size_t)nxt.pn * ksl : cA; const char* nB = has_next ? (const char*)g.Bt + (size_t)nxt.pn * bts + (size_t)nxt.pn * ksl + (gdv ? (size_t)(nxt.pm / gdv) * gst : 0) : cB;
;         GPROBE_END(2); GPROBE_BEGIN(1);
;         for (int t = 0; t < nt; t += 2) {
;             const bool last = (t == nt - 2);
;             const char* a1 = cA + (size_t)(t + 1) * kstep;
;             const char* a2 = last ? nA : cA + (size_t)(t + 2) * kstep; const char* b2 = last ? nB : cB + (size_t)(t + 2) * kstep;
;             const char* a3 = a2 + kstep; const char* b3 = b2 + kstep;
;             if (last && has_next) S.a_ready(nxt);
;             if constexpr (SP2) {
;             PG8_LDB(B0, 0, 0); PG8_LDB(B1, 0, 1); PG8_SCHED; PG8_LDA(At, 0, 0); PG8_STAGE(PG8_SA(1, 1), a1 + hstep, voffA);
;             PG8_WAIT_V(8); PG8_WAIT_L(0); PG8_BAR; PG8_MMA(0, 0, At, B0); PG8_MMA(0, 1, At, B1); PG8_BAR; PG8_SCHED;
;             PG8_LDA(At, 0, 1); PG8_STAGE(PG8_SB(0, 0), b2, voffB); PG8_STAGE(PG8_SB(0, 1), b2 + hstep, voffB); PG8_STAGE(PG8_SA(0, 0), a2, voffA);
;             PG8_WAIT_V(8); PG8_WAIT_L(0); PG8_BAR; PG8_MMA(1, 0, At, B0); PG8_MMA(1, 1, At, B1); PG8_BAR; PG8_SCHED;
;     ...
; #pragma unroll
;         for (int a = 0; a < 2; ++a)
; #pragma unroll
;             for (int b = 0; b < 2; ++b)
; #pragma unroll
;                 for (int m = 0; m < 4; ++m)
; #pragma unroll
;                     for (int n = 0; n < 2; ++n) acc[a][b][m][n] = (f32x4){0.f, 0.f, 0.f, 0.f};
.LBB0_1062:
	s_ashr_i32 s13, s12, 31
	s_lshl_b64 s[16:17], s[12:13], 20
	v_readlane_b32 s22, v254, 34
	v_readlane_b32 s23, v254, 35
	s_add_u32 s16, s22, s16
	s_addc_u32 s17, s23, s17
	s_and_b64 s[22:23], s[14:15], exec
	s_cselect_b32 s13, s17, s27
	s_cselect_b32 s24, s16, s26
	s_ashr_i32 s11, s10, 31
	s_lshl_b64 s[22:23], s[10:11], 20
	s_add_u32 s22, s2, s22
	s_addc_u32 s23, s20, s23
	s_and_b64 s[44:45], s[14:15], exec
	s_cselect_b32 s11, s23, s31
	s_cselect_b32 s25, s22, s30
	s_add_u32 s26, s26, 0x80080
	s_addc_u32 s27, s27, 0
	s_add_u32 s44, s30, 0x100
	s_addc_u32 s45, s31, 0
	s_mov_b32 s46, -2
	s_add_u32 s30, s26, 0xfff80080
	s_addc_u32 s31, s27, -1
	s_add_i32 s47, 0, 0x10000
	s_cmp_eq_u32 s46, 28
	s_cselect_b32 s49, s13, s31
	s_cselect_b32 s48, s24, s30
	s_cselect_b32 s31, s11, s45
	s_cselect_b32 s30, s25, s44
	s_add_i32 s52, 0, 0x14000
	v_add_u32_e32 v152, s47, v137
	v_add_u32_e32 v168, s52, v137
	ds_read_b128 v[140:143], v152
	ds_read_b128 v[144:147], v152 offset:1024
	ds_read_b128 v[148:151], v152 offset:2048
	ds_read_b128 v[152:155], v152 offset:3072
	ds_read_b128 v[156:159], v168
	ds_read_b128 v[160:163], v168 offset:1024
	ds_read_b128 v[164:167], v168 offset:2048
	ds_read_b128 v[168:171], v168 offset:3072
	v_lshl_add_u64 v[192:193], s[26:27], 0, v[132:133]
	s_add_i32 m0, s36, 0xc000
	ds_read_b128 v[172:175], v139
	ds_read_b128 v[176:179], v139 offset:1024
	ds_read_b128 v[180:183], v139 offset:2048
	ds_read_b128 v[184:187], v139 offset:3072
	ds_read_b128 v[188:191], v139 offset:4096
	ds_read_b128 v[198:201], v139 offset:5120
	ds_read_b128 v[202:205], v139 offset:6144
	ds_read_b128 v[206:209], v139 offset:7168
	global_load_lds_dwordx4 v[192:193], off
	v_lshl_add_u64 v[192:193], s[26:27], 0, v[134:135]
	s_add_i32 m0, s36, 0xe000
	s_nop 0
	global_load_lds_dwordx4 v[192:193], off
	s_waitcnt vmcnt(8)
	s_waitcnt lgkmcnt(0)
	s_barrier
	s_setprio 1
	s_waitcnt lgkmcnt(0)
	v_mfma_f32_16x16x32_bf16 v[126:129], v[140:143], v[172:175], 0
	v_mfma_f32_16x16x32_bf16 v[122:125], v[148:151], v[172:175], 0
	v_mfma_f32_16x16x32_bf16 v[110:113], v[140:143], v[180:183], 0
	v_mfma_f32_16x16x32_bf16 v[106:109], v[148:151], v[180:183], 0
	v_mfma_f32_16x16x32_bf16 v[94:97], v[140:143], v[188:191], 0
	v_mfma_f32_16x16x32_bf16 v[90:93], v[148:151], v[188:191], 0
	v_mfma_f32_16x16x32_bf16 v[78:81], v[140:143], v[202:205], 0
	v_mfma_f32_16x16x32_bf16 v[74:77], v[148:151], v[202:205], 0
	v_mfma_f32_16x16x32_bf16 v[126:129], v[144:147], v[176:179], v[126:129]
	v_mfma_f32_16x16x32_bf16 v[122:125], v[152:155], v[176:179], v[122:125]
	v_mfma_f32_16x16x32_bf16 v[110:113], v[144:147], v[184:187], v[110:113]
	v_mfma_f32_16x16x32_bf16 v[106:109], v[152:155], v[184:187], v[106:109]
	v_mfma_f32_16x16x32_bf16 v[94:97], v[144:147], v[198:201], v[94:97]
	v_mfma_f32_16x16x32_bf16 v[90:93], v[152:155], v[198:201], v[90:93]
	v_mfma_f32_16x16x32_bf16 v[78:81], v[144:147], v[206:209], v[78:81]
	v_mfma_f32_16x16x32_bf16 v[74:77], v[152:155], v[206:209], v[74:77]
	s_setprio 0
	s_setprio 1
	v_mfma_f32_16x16x32_bf16 v[118:121], v[156:159], v[172:175], 0
	v_mfma_f32_16x16x32_bf16 v[114:117], v[164:167], v[172:175], 0
	v_mfma_f32_16x16x32_bf16 v[102:105], v[156:159], v[180:183], 0
	v_mfma_f32_16x16x32_bf16 v[98:101], v[164:167], v[180:183], 0
	v_mfma_f32_16x16x32_bf16 v[86:89], v[156:159], v[188:191], 0
	v_mfma_f32_16x16x32_bf16 v[82:85], v[164:167], v[188:191], 0
	v_mfma_f32_16x16x32_bf16 v[70:73], v[156:159], v[202:205], 0
	v_mfma_f32_16x16x32_bf16 v[66:69], v[164:167], v[202:205], 0
	v_mfma_f32_16x16x32_bf16 v[118:121], v[160:163], v[176:179], v[118:121]
	v_mfma_f32_16x16x32_bf16 v[114:117], v[168:171], v[176:179], v[114:117]
	v_mfma_f32_16x16x32_bf16 v[102:105], v[160:163], v[184:187], v[102:105]
	v_mfma_f32_16x16x32_bf16 v[98:101], v[168:171], v[184:187], v[98:101]
	v_mfma_f32_16x16x32_bf16 v[86:89], v[160:163], v[198:201], v[86:89]
	v_mfma_f32_16x16x32_bf16 v[82:85], v[168:171], v[198:201], v[82:85]
	v_mfma_f32_16x16x32_bf16 v[70:73], v[160:163], v[206:209], v[70:73]
	v_mfma_f32_16x16x32_bf16 v[66:69], v[168:171], v[206:209], v[66:69]
	s_setprio 0
	s_barrier
	s_add_i32 s47, s47, s33
	v_lshl_add_u64 v[192:193], s[30:31], 0, v[32:33]
	s_mov_b32 m0, s47
	ds_read_b128 v[172:175], v139 offset:16384
	ds_read_b128 v[176:179], v139 offset:17408
	ds_read_b128 v[180:183], v139 offset:18432
	ds_read_b128 v[184:187], v139 offset:19456
	ds_read_b128 v[188:191], v139 offset:20480
	ds_read_b128 v[198:201], v139 offset:21504
	ds_read_b128 v[202:205], v139 offset:22528
	ds_read_b128 v[206:209], v139 offset:23552
	global_load_lds_dwordx4 v[192:193], off
	s_add_i32 m0, s47, 0x2000
	s_add_u32 s50, s30, 0x80000
	v_lshl_add_u64 v[210:211], s[30:31], 0, v[130:131]
	s_addc_u32 s51, s31, 0
	s_add_i32 s47, s52, s33
	global_load_lds_dwordx4 v[210:211], off
	v_lshl_add_u64 v[212:213], s[50:51], 0, v[32:33]
	s_mov_b32 m0, s47
	v_lshl_add_u64 v[214:215], s[48:49], 0, v[130:131]
	global_load_lds_dwordx4 v[212:213], off
	v_lshl_add_u64 v[212:213], s[50:51], 0, v[130:131]
	s_add_i32 m0, s47, 0x2000
	s_nop 0
	global_load_lds_dwordx4 v[212:213], off
	v_lshl_add_u64 v[212:213], s[48:49], 0, v[32:33]
	s_mov_b32 m0, s36
	s_nop 0
	global_load_lds_dwordx4 v[212:213], off
	s_mov_b32 m0, s37
	s_nop 0
	global_load_lds_dwordx4 v[214:215], off
	s_waitcnt vmcnt(8)
	s_waitcnt lgkmcnt(0)
	s_barrier
; #define PG8_STAGE(bufoff, gbase, voff) do { _Pragma("unroll") for (int _i = 0; _i < 2; ++_i) \
;         __builtin_amdgcn_global_load_lds((const unsigned*)((const char*)(gbase) + (voff)[_i]), (PG8_LAS unsigned*)(lds + (bufoff) + ldsw + _i * 8192), 16, 0, 0); } while (0)
; #define PG8_LDA(dst, b, h) do { _Pragma("unroll") for (int m = 0; m < 4; ++m) _Pragma("unroll") for (int k = 0; k < 2; ++k) dst[m][k] = *(const PG8_LAS bf16x8*)(lds + PG8_SA(b, h) + aoff + m * 2048 + k * 1024); } while (0)
; #define PG8_LDB(dst, b, h) do { _Pragma("unroll") for (int n = 0; n < 2; ++n) _Pragma("unroll") for (int k = 0; k < 2; ++k) dst[n][k] = *(const PG8_LAS bf16x8*)(lds + PG8_SB(b, h) + boff + n * 2048 + k * 1024); } while (0)
; #define PG8_MMA(ai, bj, At, Bt) do { __builtin_amdgcn_s_setprio(1); _Pragma("unroll") for (int m = 0; m < 4; ++m) _Pragma("unroll") for (int n = 0; n < 2; ++n) _Pragma("unroll") for (int k = 0; k < 2; ++k) \
;         acc[ai][bj][m][n] = __builtin_amdgcn_mfma_f32_16x16x32_bf16(Bt[n][k], At[m][k], acc[ai][bj][m][n], 0, 0, 0); __builtin_amdgcn_s_setprio(0); } while (0)
; #define PG8_WAIT_V(n) asm volatile("s_waitcnt vmcnt(" #n ")" ::: "memory")
; #define PG8_WAIT_L(n) asm volatile("s_waitcnt lgkmcnt(" #n ")" ::: "memory")
; #define PG8_BAR __builtin_amdgcn_s_barrier()
; #define PG8_SCHED __builtin_amdgcn_sched_barrier(0)
; template <class Epi, class Sched, bool ALIGN_EPI = false, bool SP2 = false, bool KHOOK = false>
; __device__ __forceinline__ void gemm_phase(PG8_LAS unsigned char* lds, const Gemm g, const Sched& S, const Epi& E, const int tid_in) {
;     ...
;             PG8_WAIT_V(8); PG8_WAIT_L(0); PG8_BAR; PG8_MMA(1, 0, At, B0); PG8_MMA(1, 1, At, B1); PG8_BAR; PG8_SCHED;
;             PG8_LDB(B0, 1, 0); PG8_LDB(B1, 1, 1); PG8_SCHED; PG8_LDA(At, 1, 0); PG8_STAGE(PG8_SA(0, 1), a2 + hstep, voffA);
;             PG8_WAIT_V(8); PG8_WAIT_L(0); PG8_BAR; PG8_MMA(0, 0, At, B0); PG8_MMA(0, 1, At, B1); PG8_BAR; PG8_SCHED;
	s_setprio 1
	s_waitcnt lgkmcnt(0)
	v_mfma_f32_16x16x32_bf16 v[62:65], v[140:143], v[172:175], 0
	v_mfma_f32_16x16x32_bf16 v[58:61], v[148:151], v[172:175], 0
	v_mfma_f32_16x16x32_bf16 v[46:49], v[140:143], v[180:183], 0
	v_mfma_f32_16x16x32_bf16 v[42:45], v[148:151], v[180:183], 0
	v_mfma_f32_16x16x32_bf16 v[28:31], v[140:143], v[188:191], 0
	v_mfma_f32_16x16x32_bf16 v[24:27], v[148:151], v[188:191], 0
	v_mfma_f32_16x16x32_bf16 v[12:15], v[140:143], v[202:205], 0
	v_mfma_f32_16x16x32_bf16 v[8:11], v[148:151], v[202:205], 0
	v_mfma_f32_16x16x32_bf16 v[62:65], v[144:147], v[176:179], v[62:65]
	v_mfma_f32_16x16x32_bf16 v[58:61], v[152:155], v[176:179], v[58:61]
	v_mfma_f32_16x16x32_bf16 v[46:49], v[144:147], v[184:187], v[46:49]
	v_mfma_f32_16x16x32_bf16 v[42:45], v[152:155], v[184:187], v[42:45]
	v_mfma_f32_16x16x32_bf16 v[28:31], v[144:147], v[198:201], v[28:31]
	v_mfma_f32_16x16x32_bf16 v[24:27], v[152:155], v[198:201], v[24:27]
	v_mfma_f32_16x16x32_bf16 v[12:15], v[144:147], v[206:209], v[12:15]
	v_mfma_f32_16x16x32_bf16 v[8:11], v[152:155], v[206:209], v[8:11]
	s_setprio 0
	s_setprio 1
	v_mfma_f32_16x16x32_bf16 v[54:57], v[156:159], v[172:175], 0
	v_mfma_f32_16x16x32_bf16 v[50:53], v[164:167], v[172:175], 0
	v_mfma_f32_16x16x32_bf16 v[38:41], v[156:159], v[180:183], 0
	v_mfma_f32_16x16x32_bf16 v[34:37], v[164:167], v[180:183], 0
	v_mfma_f32_16x16x32_bf16 v[20:23], v[156:159], v[188:191], 0
	v_mfma_f32_16x16x32_bf16 v[16:19], v[164:167], v[188:191], 0
	v_mfma_f32_16x16x32_bf16 v[4:7], v[156:159], v[202:205], 0
	v_mfma_f32_16x16x32_bf16 v[0:3], v[164:167], v[202:205], 0
	v_mfma_f32_16x16x32_bf16 v[54:57], v[160:163], v[176:179], v[54:57]
	v_mfma_f32_16x16x32_bf16 v[50:53], v[168:171], v[176:179], v[50:53]
	v_mfma_f32_16x16x32_bf16 v[38:41], v[160:163], v[184:187], v[38:41]
	v_mfma_f32_16x16x32_bf16 v[34:37], v[168:171], v[184:187], v[34:37]
	v_mfma_f32_16x16x32_bf16 v[20:23], v[160:163], v[198:201], v[20:23]
	v_mfma_f32_16x16x32_bf16 v[16:19], v[168:171], v[198:201], v[16:19]
	v_mfma_f32_16x16x32_bf16 v[4:7], v[160:163], v[206:209], v[4:7]
	v_mfma_f32_16x16x32_bf16 v[0:3], v[168:171], v[206:209], v[0:3]
	s_setprio 0
	s_barrier
	s_add_i32 s47, 0, 0x18000
	s_add_i32 s50, 0, 0x1c000
	v_add_u32_e32 v152, s47, v137
	v_add_u32_e32 v168, s50, v137
	ds_read_b128 v[140:143], v152
	ds_read_b128 v[144:147], v152 offset:1024
	ds_read_b128 v[148:151], v152 offset:2048
	ds_read_b128 v[152:155], v152 offset:3072
	ds_read_b128 v[156:159], v168
	ds_read_b128 v[160:163], v168 offset:1024
	ds_read_b128 v[164:167], v168 offset:2048
	ds_read_b128 v[168:171], v168 offset:3072
	s_add_u32 s48, s48, 0x80000
	s_addc_u32 s49, s49, 0
	s_mov_b32 m0, s38
	v_lshl_add_u64 v[216:217], s[48:49], 0, v[32:33]
	ds_read_b128 v[172:175], v139 offset:32768
	ds_read_b128 v[176:179], v139 offset:33792
	ds_read_b128 v[180:183], v139 offset:34816
	ds_read_b128 v[184:187], v139 offset:35840
	ds_read_b128 v[188:191], v139 offset:36864
	ds_read_b128 v[198:201], v139 offset:37888
	ds_read_b128 v[202:205], v139 offset:38912
	ds_read_b128 v[206:209], v139 offset:39936
	global_load_lds_dwordx4 v[216:217], off
	v_lshl_add_u64 v[216:217], s[48:49], 0, v[130:131]
	s_mov_b32 m0, s39
	s_nop 0
	global_load_lds_dwordx4 v[216:217], off
	s_waitcnt vmcnt(8)
	s_waitcnt lgkmcnt(0)
	s_barrier
	s_setprio 1
	s_waitcnt lgkmcnt(0)
	v_mfma_f32_16x16x32_bf16 v[126:129], v[140:143], v[172:175], v[126:129]
	v_mfma_f32_16x16x32_bf16 v[122:125], v[148:151], v[172:175], v[122:125]
	v_mfma_f32_16x16x32_bf16 v[110:113], v[140:143], v[180:183], v[110:113]
	v_mfma_f32_16x16x32_bf16 v[106:109], v[148:151], v[180:183], v[106:109]
	v_mfma_f32_16x16x32_bf16 v[94:97], v[140:143], v[188:191], v[94:97]
	v_mfma_f32_16x16x32_bf16 v[90:93], v[148:151], v[188:191], v[90:93]
	v_mfma_f32_16x16x32_bf16 v[78:81], v[140:143], v[202:205], v[78:81]
	v_mfma_f32_16x16x32_bf16 v[74:77], v[148:151], v[202:205], v[74:77]
	v_mfma_f32_16x16x32_bf16 v[126:129], v[144:147], v[176:179], v[126:129]
	v_mfma_f32_16x16x32_bf16 v[122:125], v[152:155], v[176:179], v[122:125]
	v_mfma_f32_16x16x32_bf16 v[110:113], v[144:147], v[184:187], v[110:113]
	v_mfma_f32_16x16x32_bf16 v[106:109], v[152:155], v[184:187], v[106:109]
	v_mfma_f32_16x16x32_bf16 v[94:97], v[144:147], v[198:201], v[94:97]
	v_mfma_f32_16x16x32_bf16 v[90:93], v[152:155], v[198:201], v[90:93]
	v_mfma_f32_16x16x32_bf16 v[78:81], v[144:147], v[206:209], v[78:81]
	v_mfma_f32_16x16x32_bf16 v[74:77], v[152:155], v[206:209], v[74:77]
	s_setprio 0
	s_setprio 1
	v_mfma_f32_16x16x32_bf16 v[118:121], v[156:159], v[172:175], v[118:121]
	v_mfma_f32_16x16x32_bf16 v[114:117], v[164:167], v[172:175], v[114:117]
	v_mfma_f32_16x16x32_bf16 v[102:105], v[156:159], v[180:183], v[102:105]
	v_mfma_f32_16x16x32_bf16 v[98:101], v[164:167], v[180:183], v[98:101]
	v_mfma_f32_16x16x32_bf16 v[86:89], v[156:159], v[188:191], v[86:89]
	v_mfma_f32_16x16x32_bf16 v[82:85], v[164:167], v[188:191], v[82:85]
	v_mfma_f32_16x16x32_bf16 v[70:73], v[156:159], v[202:205], v[70:73]
	v_mfma_f32_16x16x32_bf16 v[66:69], v[164:167], v[202:205], v[66:69]
	v_mfma_f32_16x16x32_bf16 v[118:121], v[160:163], v[176:179], v[118:121]
	v_mfma_f32_16x16x32_bf16 v[114:117], v[168:171], v[176:179], v[114:117]
	v_mfma_f32_16x16x32_bf16 v[102:105], v[160:163], v[184:187], v[102:105]
	v_mfma_f32_16x16x32_bf16 v[98:101], v[168:171], v[184:187], v[98:101]
	v_mfma_f32_16x16x32_bf16 v[86:89], v[160:163], v[198:201], v[86:89]
	v_mfma_f32_16x16x32_bf16 v[82:85], v[168:171], v[198:201], v[82:85]
	v_mfma_f32_16x16x32_bf16 v[70:73], v[160:163], v[206:209], v[70:73]
	v_mfma_f32_16x16x32_bf16 v[66:69], v[168:171], v[206:209], v[66:69]
	s_setprio 0
	s_barrier
; #define PG8_STAGE(bufoff, gbase, voff) do { _Pragma("unroll") for (int _i = 0; _i < 2; ++_i) \
;         __builtin_amdgcn_global_load_lds((const unsigned*)((const char*)(gbase) + (voff)[_i]), (PG8_LAS unsigned*)(lds + (bufoff) + ldsw + _i * 8192), 16, 0, 0); } while (0)
; #define PG8_LDA(dst, b, h) do { _Pragma("unroll") for (int m = 0; m < 4; ++m) _Pragma("unroll") for (int k = 0; k < 2; ++k) dst[m][k] = *(const PG8_LAS bf16x8*)(lds + PG8_SA(b, h) + aoff + m * 2048 + k * 1024); } while (0)
; #define PG8_MMA(ai, bj, At, Bt) do { __builtin_amdgcn_s_setprio(1); _Pragma("unroll") for (int m = 0; m < 4; ++m) _Pragma("unroll") for (int n = 0; n < 2; ++n) _Pragma("unroll") for (int k = 0; k < 2; ++k) \
;         acc[ai][bj][m][n] = __builtin_amdgcn_mfma_f32_16x16x32_bf16(Bt[n][k], At[m][k], acc[ai][bj][m][n], 0, 0, 0); __builtin_amdgcn_s_setprio(0); } while (0)
; #define PG8_WAIT_V(n) asm volatile("s_waitcnt vmcnt(" #n ")" ::: "memory")
; #define PG8_WAIT_L(n) asm volatile("s_waitcnt lgkmcnt(" #n ")" ::: "memory")
; #define PG8_BAR __builtin_amdgcn_s_barrier()
; #define PG8_SCHED __builtin_amdgcn_sched_barrier(0)
; template <class Epi, class Sched, bool ALIGN_EPI = false, bool SP2 = false, bool KHOOK = false>
; __device__ __forceinline__ void gemm_phase(PG8_LAS unsigned char* lds, const Gemm g, const Sched& S, const Epi& E, const int tid_in) {
;     ...
;         for (int t = 0; t < nt; t += 2) {
;             const bool last = (t == nt - 2);
;             const char* a1 = cA + (size_t)(t + 1) * kstep;
;             const char* a2 = last ? nA : cA + (size_t)(t + 2) * kstep; const char* b2 = last ? nB : cB + (size_t)(t + 2) * kstep;
;     ...
;             PG8_LDA(At, 1, 1); PG8_STAGE(PG8_SB(1, 0), b3, voffB); PG8_STAGE(PG8_SB(1, 1), b3 + hstep, voffB); PG8_STAGE(PG8_SA(1, 0), a3, voffA);
;             PG8_WAIT_V(8); PG8_WAIT_L(0); PG8_BAR; PG8_MMA(1, 0, At, B0); PG8_MMA(1, 1, At, B1); PG8_BAR; PG8_SCHED;
	s_add_i32 s47, s47, s33
	v_lshl_add_u64 v[192:193], v[192:193], 0, s[90:91]
	s_mov_b32 m0, s47
	ds_read_b128 v[172:175], v139 offset:49152
	ds_read_b128 v[176:179], v139 offset:50176
	ds_read_b128 v[180:183], v139 offset:51200
	ds_read_b128 v[184:187], v139 offset:52224
	ds_read_b128 v[188:191], v139 offset:53248
	ds_read_b128 v[198:201], v139 offset:54272
	ds_read_b128 v[202:205], v139 offset:55296
	ds_read_b128 v[206:209], v139 offset:56320
	global_load_lds_dwordx4 v[192:193], off
	s_add_i32 m0, s47, 0x2000
	s_add_u32 s30, s30, 0x80080
	v_lshl_add_u64 v[192:193], v[210:211], 0, s[90:91]
	s_addc_u32 s31, s31, 0
	s_add_i32 s47, s50, s33
	global_load_lds_dwordx4 v[192:193], off
	v_lshl_add_u64 v[192:193], s[30:31], 0, v[32:33]
	s_mov_b32 m0, s47
	s_nop 0
	global_load_lds_dwordx4 v[192:193], off
	v_lshl_add_u64 v[192:193], s[30:31], 0, v[130:131]
	s_add_i32 m0, s47, 0x2000
	s_nop 0
	global_load_lds_dwordx4 v[192:193], off
	v_lshl_add_u64 v[192:193], v[212:213], 0, s[90:91]
	s_mov_b32 m0, s40
	s_nop 0
	global_load_lds_dwordx4 v[192:193], off
	v_lshl_add_u64 v[192:193], v[214:215], 0, s[90:91]
	s_mov_b32 m0, s41
	s_nop 0
	global_load_lds_dwordx4 v[192:193], off
	s_waitcnt vmcnt(8)
	s_waitcnt lgkmcnt(0)
	s_barrier
	s_setprio 1
	s_waitcnt lgkmcnt(0)
	v_mfma_f32_16x16x32_bf16 v[62:65], v[140:143], v[172:175], v[62:65]
	v_mfma_f32_16x16x32_bf16 v[58:61], v[148:151], v[172:175], v[58:61]
	v_mfma_f32_16x16x32_bf16 v[46:49], v[140:143], v[180:183], v[46:49]
	v_mfma_f32_16x16x32_bf16 v[42:45], v[148:151], v[180:183], v[42:45]
	v_mfma_f32_16x16x32_bf16 v[28:31], v[140:143], v[188:191], v[28:31]
	v_mfma_f32_16x16x32_bf16 v[24:27], v[148:151], v[188:191], v[24:27]
	v_mfma_f32_16x16x32_bf16 v[12:15], v[140:143], v[202:205], v[12:15]
	v_mfma_f32_16x16x32_bf16 v[8:11], v[148:151], v[202:205], v[8:11]
	v_mfma_f32_16x16x32_bf16 v[62:65], v[144:147], v[176:179], v[62:65]
	v_mfma_f32_16x16x32_bf16 v[58:61], v[152:155], v[176:179], v[58:61]
	v_mfma_f32_16x16x32_bf16 v[46:49], v[144:147], v[184:187], v[46:49]
	v_mfma_f32_16x16x32_bf16 v[42:45], v[152:155], v[184:187], v[42:45]
	v_mfma_f32_16x16x32_bf16 v[28:31], v[144:147], v[198:201], v[28:31]
	v_mfma_f32_16x16x32_bf16 v[24:27], v[152:155], v[198:201], v[24:27]
	v_mfma_f32_16x16x32_bf16 v[12:15], v[144:147], v[206:209], v[12:15]
	v_mfma_f32_16x16x32_bf16 v[8:11], v[152:155], v[206:209], v[8:11]
	s_setprio 0
	s_setprio 1
	v_mfma_f32_16x16x32_bf16 v[54:57], v[156:159], v[172:175], v[54:57]
	v_mfma_f32_16x16x32_bf16 v[50:53], v[164:167], v[172:175], v[50:53]
	v_mfma_f32_16x16x32_bf16 v[38:41], v[156:159], v[180:183], v[38:41]
	v_mfma_f32_16x16x32_bf16 v[34:37], v[164:167], v[180:183], v[34:37]
	v_mfma_f32_16x16x32_bf16 v[20:23], v[156:159], v[188:191], v[20:23]
	v_mfma_f32_16x16x32_bf16 v[16:19], v[164:167], v[188:191], v[16:19]
	v_mfma_f32_16x16x32_bf16 v[4:7], v[156:159], v[202:205], v[4:7]
	v_mfma_f32_16x16x32_bf16 v[0:3], v[164:167], v[202:205], v[0:3]
	v_mfma_f32_16x16x32_bf16 v[54:57], v[160:163], v[176:179], v[54:57]
	v_mfma_f32_16x16x32_bf16 v[50:53], v[168:171], v[176:179], v[50:53]
	v_mfma_f32_16x16x32_bf16 v[38:41], v[160:163], v[184:187], v[38:41]
	v_mfma_f32_16x16x32_bf16 v[34:37], v[168:171], v[184:187], v[34:37]
	v_mfma_f32_16x16x32_bf16 v[20:23], v[160:163], v[198:201], v[20:23]
	v_mfma_f32_16x16x32_bf16 v[16:19], v[168:171], v[198:201], v[16:19]
	v_mfma_f32_16x16x32_bf16 v[4:7], v[160:163], v[206:209], v[4:7]
	v_mfma_f32_16x16x32_bf16 v[0:3], v[168:171], v[206:209], v[0:3]
	s_setprio 0
	s_barrier
	s_add_i32 s46, s46, 2
	s_add_u32 s26, s26, 0x100
	s_addc_u32 s27, s27, 0
	s_add_u32 s44, s44, 0x100
	s_addc_u32 s45, s45, 0
	s_cmp_gt_u32 s46, 29

; __global__ void __launch_bounds__(NWAVES * 64, 2) trunk_fwd(Params P) {
	.amdhsa_kernel _Z9trunk_fwd6Params
		.amdhsa_group_segment_fixed_size 0
		.amdhsa_private_segment_fixed_size 0
		.amdhsa_kernarg_size 440
		.amdhsa_user_sgpr_count 2
		.amdhsa_user_sgpr_dispatch_ptr 0
		.amdhsa_user_sgpr_queue_ptr 0
		.amdhsa_user_sgpr_kernarg_segment_ptr 1
		.amdhsa_user_sgpr_dispatch_id 0
		.amdhsa_user_sgpr_kernarg_preload_length 0
		.amdhsa_user_sgpr_kernarg_preload_offset 0
		.amdhsa_user_sgpr_private_segment_size 0
		.amdhsa_uses_dynamic_stack 0
		.amdhsa_enable_private_segment 0
		.amdhsa_system_sgpr_workgroup_id_x 1
		.amdhsa_system_sgpr_workgroup_id_y 0
		.amdhsa_system_sgpr_workgroup_id_z 0
		.amdhsa_system_sgpr_workgroup_info 0
		.amdhsa_system_vgpr_workitem_id 0
		.amdhsa_next_free_vgpr 256
		.amdhsa_next_free_sgpr 102
		.amdhsa_accum_offset 256
		.amdhsa_reserve_vcc 1
		.amdhsa_float_round_mode_32 0
		.amdhsa_float_round_mode_16_64 0
		.amdhsa_float_denorm_mode_32 3
		.amdhsa_float_denorm_mode_16_64 3
		.amdhsa_dx10_clamp 1
		.amdhsa_ieee_mode 1
		.amdhsa_fp16_overflow 0
		.amdhsa_tg_split 0
		.amdhsa_exception_fp_ieee_invalid_op 0
		.amdhsa_exception_fp_denorm_src 0
		.amdhsa_exception_fp_ieee_div_zero 0
		.amdhsa_exception_fp_ieee_overflow 0
		.amdhsa_exception_fp_ieee_underflow 0
		.amdhsa_exception_fp_ieee_inexact 0
		.amdhsa_exception_int_div_zero 0
	.end_amdhsa_kernel

; __global__ void __launch_bounds__(NWAVES * 64, 2) trunk_fwd(Params P) {
amdhsa.kernels:
  - .agpr_count:     0
    .args:
      - .offset:         0
        .size:           184
        .value_kind:     by_value
      - .offset:         184
        .size:           4
        .value_kind:     hidden_block_count_x
      - .offset:         188
        .size:           4
        .value_kind:     hidden_block_count_y
      - .offset:         192
        .size:           4
        .value_kind:     hidden_block_count_z
      - .offset:         196
        .size:           2
        .value_kind:     hidden_group_size_x
      - .offset:         198
        .size:           2
        .value_kind:     hidden_group_size_y
      - .offset:         200
        .size:           2
        .value_kind:     hidden_group_size_z
      - .offset:         202
        .size:           2
        .value_kind:     hidden_remainder_x
      - .offset:         204
        .size:           2
        .value_kind:     hidden_remainder_y
      - .offset:         206
        .size:           2
        .value_kind:     hidden_remainder_z
      - .offset:         224
        .size:           8
        .value_kind:     hidden_global_offset_x
      - .offset:         232
        .size:           8
        .value_kind:     hidden_global_offset_y
      - .offset:         240
        .size:           8
        .value_kind:     hidden_global_offset_z
      - .offset:         248
        .size:           2
        .value_kind:     hidden_grid_dims
      - .offset:         304
        .size:           4
        .value_kind:     hidden_dynamic_lds_size
    .group_segment_fixed_size: 0
    .kernarg_segment_align: 8
    .kernarg_segment_size: 440
    .language:       OpenCL C
    .language_version:
      - 2
      - 0
    .max_flat_workgroup_size: 512
    .name:           _Z9trunk_fwd6Params
    .private_segment_fixed_size: 0
    .sgpr_count:     108
    .sgpr_spill_count: 278
    .symbol:         _Z9trunk_fwd6Params.kd
    .uniform_work_group_size: 1
    .uses_dynamic_stack: false
    .vgpr_count:     256
    .vgpr_spill_count: 0
    .wavefront_size: 64
